# non-temporal (nt) hint on the P1 PROJ and P5 U epilogue stores (streamed outputs that are next read after a grid barrier), on top of v37
# speedup vs baseline: 1.0133x; 1.0133x over previous
; __device__ __forceinline__ u32x4 pack8(const float* f) { u32x4 w; w.x = cvt_pk_bf16(f[0], f[1]); w.y = cvt_pk_bf16(f[2], f[3]); w.z = cvt_pk_bf16(f[4], f[5]); w.w = cvt_pk_bf16(f[6], f[7]); return w; }
;     __device__ __forceinline__ void operator()(AccT& acc, const Unit& u, int wr, int wc, int fr, int fq) const {
;         const bool gate = u.pn >= 5;
;         const int col0 = u.pn * 256 + wc * 32 + 8 * fq;
;         f32x4 gb[2][2];
; #pragma unroll
;         for (int bj = 0; bj < 2; ++bj)
; #pragma unroll
;             for (int n = 0; n < 2; ++n) gb[bj][n] = gate ? *(const f32x4*)(gbias + (col0 - 1280) + bj * 128 + 4 * n) : (f32x4){0.f, 0.f, 0.f, 0.f};
;         float rsv[2][4];
; #pragma unroll
;         for (int ai = 0; ai < 2; ++ai)
; #pragma unroll
;             for (int m = 0; m < 4; ++m) rsv[ai][m] = ssq[u.pm * 256 + ai * 128 + wr * 64 + m * 16 + fr];
; #pragma unroll
;         for (int ai = 0; ai < 2; ++ai)
; #pragma unroll
;             for (int m = 0; m < 4; ++m) {
;                 const int row = u.pm * 256 + ai * 128 + wr * 64 + m * 16 + fr;
;                 const float rs = __builtin_amdgcn_rsqf(rsv[ai][m] * (1.0f / 1024.0f) + EPS);
;                 bf16_t* rowp = P + (size_t)row * INW + col0;
; #pragma unroll
;                 for (int bj = 0; bj < 2; ++bj) {
;                     float v[8];
; #pragma unroll
;                     for (int n = 0; n < 2; ++n)
; #pragma unroll
;                         for (int j = 0; j < 4; ++j) {
;                             float x = acc[ai][bj][m][n][j] * rs;
;                             if (gate) { x += gb[bj][n][j]; x = __builtin_amdgcn_rcpf(1.0f + __builtin_amdgcn_exp2f(-LOG2E * x)); }
;                             v[n * 4 + j] = x;
;                         }
;                     *(u32x4*)(rowp + bj * 128) = pack8(v);
;                 }
.LBB0_185:
	s_lshl_b32 s0, s49, 8
	s_add_i32 s0, s0, s33
	v_add_u32_e32 v160, s0, v160
	v_ashrrev_i32_e32 v161, 31, v160
	v_lshl_add_u64 v[156:157], v[160:161], 2, s[46:47]
	global_load_dword v161, v[156:157], off
	global_load_dword v179, v[156:157], off offset:64
	global_load_dword v177, v[156:157], off offset:128
	global_load_dword v175, v[156:157], off offset:192
	global_load_dword v173, v[156:157], off offset:512
	global_load_dword v171, v[156:157], off offset:576
	global_load_dword v169, v[156:157], off offset:640
	global_load_dword v167, v[156:157], off offset:704
	v_add_u32_e32 v178, 16, v160
	v_add_u32_e32 v176, 32, v160
	v_add_u32_e32 v174, 48, v160
	v_add_u32_e32 v172, 0x80, v160
	v_add_u32_e32 v170, 0x90, v160
	v_add_u32_e32 v168, 0xa0, v160
	v_add_u32_e32 v166, 0xb0, v160
	v_lshlrev_b64 v[158:159], 1, v[158:159]
	s_andn2_b64 vcc, exec, s[40:41]
	s_waitcnt vmcnt(0) lgkmcnt(0)
	s_cmp_eq_u64 s[42:43], 0
	s_cbranch_scc1 .Lmy_p1_nongate
	v_mul_f32_e32 v214, 0xbfb8aa3b, v52
	v_mul_f32_e32 v215, 0xbfb8aa3b, v53
	v_mul_f32_e32 v216, 0xbfb8aa3b, v54
	v_mul_f32_e32 v217, 0xbfb8aa3b, v55
	v_mul_f32_e32 v218, 0xbfb8aa3b, v44
	v_mul_f32_e32 v219, 0xbfb8aa3b, v45
	v_mul_f32_e32 v220, 0xbfb8aa3b, v46
	v_mul_f32_e32 v221, 0xbfb8aa3b, v47
	v_mul_f32_e32 v238, 0xbfb8aa3b, v40
	v_mul_f32_e32 v239, 0xbfb8aa3b, v41
	v_mul_f32_e32 v240, 0xbfb8aa3b, v42
	v_mul_f32_e32 v241, 0xbfb8aa3b, v43
	v_mul_f32_e32 v242, 0xbfb8aa3b, v32
	v_mul_f32_e32 v243, 0xbfb8aa3b, v33
	v_mul_f32_e32 v244, 0xbfb8aa3b, v34
	v_mul_f32_e32 v245, 0xbfb8aa3b, v35
	v_fmamk_f32 v156, v161, 0x3a800000, v223
	v_rsq_f32_e32 v180, v156
	s_nop 0
	v_mul_f32_e32 v180, 0xbfb8aa3b, v180
	v_mov_b64_e32 v[156:157], s[84:85]
	v_mad_i64_i32 v[160:161], s[0:1], v160, s89, v[156:157]
	v_lshl_add_u64 v[160:161], v[160:161], 0, v[158:159]
	v_fma_f32 v206, v142, v180, v214
	v_fma_f32 v207, v143, v180, v215
	v_fma_f32 v208, v144, v180, v216
	v_fma_f32 v209, v145, v180, v217
	v_fma_f32 v210, v138, v180, v218
	v_fma_f32 v211, v139, v180, v219
	v_fma_f32 v212, v140, v180, v220
	v_fma_f32 v213, v141, v180, v221
	v_exp_f32_e32 v206, v206
	v_exp_f32_e32 v207, v207
	v_exp_f32_e32 v208, v208
	v_exp_f32_e32 v209, v209
	v_exp_f32_e32 v210, v210
	v_exp_f32_e32 v211, v211
	v_exp_f32_e32 v212, v212
	v_exp_f32_e32 v213, v213
	v_add_f32_e32 v206, 1.0, v206
	v_add_f32_e32 v207, 1.0, v207
	v_add_f32_e32 v208, 1.0, v208
	v_add_f32_e32 v209, 1.0, v209
	v_add_f32_e32 v210, 1.0, v210
	v_add_f32_e32 v211, 1.0, v211
	v_add_f32_e32 v212, 1.0, v212
	v_add_f32_e32 v213, 1.0, v213
	v_rcp_f32_e32 v142, v206
	v_rcp_f32_e32 v143, v207
	v_rcp_f32_e32 v144, v208
	v_rcp_f32_e32 v145, v209
	v_rcp_f32_e32 v181, v210
	v_rcp_f32_e32 v182, v211
	v_rcp_f32_e32 v183, v212
	v_rcp_f32_e32 v141, v213
	v_cvt_pk_bf16_f32 v138, v142, v143
	v_cvt_pk_bf16_f32 v139, v144, v145
	v_cvt_pk_bf16_f32 v140, v181, v182
	v_cvt_pk_bf16_f32 v141, v183, v141
	global_store_dwordx4 v[160:161], v[138:141], off nt
	s_nop 1
	v_fma_f32 v206, v134, v180, v238
	v_fma_f32 v207, v135, v180, v239
	v_fma_f32 v208, v136, v180, v240
	v_fma_f32 v209, v137, v180, v241
	v_fma_f32 v210, v130, v180, v242
	v_fma_f32 v211, v131, v180, v243
	v_fma_f32 v212, v132, v180, v244
	v_fma_f32 v213, v133, v180, v245
	v_exp_f32_e32 v206, v206
	v_exp_f32_e32 v207, v207
	v_exp_f32_e32 v208, v208
	v_exp_f32_e32 v209, v209
	v_exp_f32_e32 v210, v210
	v_exp_f32_e32 v211, v211
	v_exp_f32_e32 v212, v212
	v_exp_f32_e32 v213, v213
	v_add_f32_e32 v206, 1.0, v206
	v_add_f32_e32 v207, 1.0, v207
	v_add_f32_e32 v208, 1.0, v208
	v_add_f32_e32 v209, 1.0, v209
	v_add_f32_e32 v210, 1.0, v210
	v_add_f32_e32 v211, 1.0, v211
	v_add_f32_e32 v212, 1.0, v212
	v_add_f32_e32 v213, 1.0, v213
	v_rcp_f32_e32 v134, v206
	v_rcp_f32_e32 v135, v207
	v_rcp_f32_e32 v136, v208
	v_rcp_f32_e32 v137, v209
	v_rcp_f32_e32 v138, v210
	v_rcp_f32_e32 v139, v211
	v_rcp_f32_e32 v140, v212
	v_rcp_f32_e32 v133, v213
	v_cvt_pk_bf16_f32 v130, v134, v135
	v_cvt_pk_bf16_f32 v131, v136, v137
	v_cvt_pk_bf16_f32 v132, v138, v139
	v_cvt_pk_bf16_f32 v133, v140, v133
	global_store_dwordx4 v[160:161], v[130:133], off offset:256 nt
	s_nop 1
	v_fmamk_f32 v130, v179, 0x3a800000, v223
	v_rsq_f32_e32 v132, v130
	s_nop 0
	v_mul_f32_e32 v132, 0xbfb8aa3b, v132
	v_mad_i64_i32 v[130:131], s[0:1], v178, s89, v[156:157]
	v_lshl_add_u64 v[130:131], v[130:131], 0, v[158:159]
	v_fma_f32 v206, v126, v132, v214
	v_fma_f32 v207, v127, v132, v215
	v_fma_f32 v208, v128, v132, v216
	v_fma_f32 v209, v129, v132, v217
	v_fma_f32 v210, v122, v132, v218
	v_fma_f32 v211, v123, v132, v219
	v_fma_f32 v212, v124, v132, v220
	v_fma_f32 v213, v125, v132, v221
	v_exp_f32_e32 v206, v206
	v_exp_f32_e32 v207, v207
	v_exp_f32_e32 v208, v208
	v_exp_f32_e32 v209, v209
	v_exp_f32_e32 v210, v210
	v_exp_f32_e32 v211, v211
	v_exp_f32_e32 v212, v212
	v_exp_f32_e32 v213, v213
	v_add_f32_e32 v206, 1.0, v206
	v_add_f32_e32 v207, 1.0, v207
	v_add_f32_e32 v208, 1.0, v208
	v_add_f32_e32 v209, 1.0, v209
	v_add_f32_e32 v210, 1.0, v210
	v_add_f32_e32 v211, 1.0, v211
	v_add_f32_e32 v212, 1.0, v212
	v_add_f32_e32 v213, 1.0, v213
	v_rcp_f32_e32 v126, v206
	v_rcp_f32_e32 v127, v207
	v_rcp_f32_e32 v128, v208
	v_rcp_f32_e32 v129, v209
	v_rcp_f32_e32 v133, v210
	v_rcp_f32_e32 v134, v211
	v_rcp_f32_e32 v135, v212
	v_rcp_f32_e32 v125, v213
	v_cvt_pk_bf16_f32 v122, v126, v127
	v_cvt_pk_bf16_f32 v123, v128, v129
	v_cvt_pk_bf16_f32 v124, v133, v134
	v_cvt_pk_bf16_f32 v125, v135, v125
	global_store_dwordx4 v[130:131], v[122:125], off nt
	s_nop 1
	v_fma_f32 v206, v118, v132, v238
	v_fma_f32 v207, v119, v132, v239
	v_fma_f32 v208, v120, v132, v240
	v_fma_f32 v209, v121, v132, v241
	v_fma_f32 v210, v114, v132, v242
; __device__ __forceinline__ u32x4 pack8(const float* f) { u32x4 w; w.x = cvt_pk_bf16(f[0], f[1]); w.y = cvt_pk_bf16(f[2], f[3]); w.z = cvt_pk_bf16(f[4], f[5]); w.w = cvt_pk_bf16(f[6], f[7]); return w; }
;     __device__ __forceinline__ void operator()(AccT& acc, const Unit& u, int wr, int wc, int fr, int fq) const {
;     ...
;         for (int ai = 0; ai < 2; ++ai)
; #pragma unroll
;             for (int m = 0; m < 4; ++m) {
;                 const int row = u.pm * 256 + ai * 128 + wr * 64 + m * 16 + fr;
;                 const float rs = __builtin_amdgcn_rsqf(rsv[ai][m] * (1.0f / 1024.0f) + EPS);
;                 bf16_t* rowp = P + (size_t)row * INW + col0;
; #pragma unroll
;                 for (int bj = 0; bj < 2; ++bj) {
;                     float v[8];
; #pragma unroll
;                     for (int n = 0; n < 2; ++n)
; #pragma unroll
;                         for (int j = 0; j < 4; ++j) {
;                             float x = acc[ai][bj][m][n][j] * rs;
;                             if (gate) { x += gb[bj][n][j]; x = __builtin_amdgcn_rcpf(1.0f + __builtin_amdgcn_exp2f(-LOG2E * x)); }
;                             v[n * 4 + j] = x;
;                         }
;                     *(u32x4*)(rowp + bj * 128) = pack8(v);
;                 }
	v_fma_f32 v211, v115, v132, v243
	v_fma_f32 v212, v116, v132, v244
	v_fma_f32 v213, v117, v132, v245
	v_exp_f32_e32 v206, v206
	v_exp_f32_e32 v207, v207
	v_exp_f32_e32 v208, v208
	v_exp_f32_e32 v209, v209
	v_exp_f32_e32 v210, v210
	v_exp_f32_e32 v211, v211
	v_exp_f32_e32 v212, v212
	v_exp_f32_e32 v213, v213
	v_add_f32_e32 v206, 1.0, v206
	v_add_f32_e32 v207, 1.0, v207
	v_add_f32_e32 v208, 1.0, v208
	v_add_f32_e32 v209, 1.0, v209
	v_add_f32_e32 v210, 1.0, v210
	v_add_f32_e32 v211, 1.0, v211
	v_add_f32_e32 v212, 1.0, v212
	v_add_f32_e32 v213, 1.0, v213
	v_rcp_f32_e32 v118, v206
	v_rcp_f32_e32 v119, v207
	v_rcp_f32_e32 v120, v208
	v_rcp_f32_e32 v121, v209
	v_rcp_f32_e32 v122, v210
	v_rcp_f32_e32 v123, v211
	v_rcp_f32_e32 v124, v212
	v_rcp_f32_e32 v117, v213
	v_cvt_pk_bf16_f32 v114, v118, v119
	v_cvt_pk_bf16_f32 v115, v120, v121
	v_cvt_pk_bf16_f32 v116, v122, v123
	v_cvt_pk_bf16_f32 v117, v124, v117
	global_store_dwordx4 v[130:131], v[114:117], off offset:256 nt
	s_nop 1
	v_fmamk_f32 v114, v177, 0x3a800000, v223
	v_rsq_f32_e32 v116, v114
	s_nop 0
	v_mul_f32_e32 v116, 0xbfb8aa3b, v116
	v_mad_i64_i32 v[114:115], s[0:1], v176, s89, v[156:157]
	v_lshl_add_u64 v[114:115], v[114:115], 0, v[158:159]
	v_fma_f32 v206, v110, v116, v214
	v_fma_f32 v207, v111, v116, v215
	v_fma_f32 v208, v112, v116, v216
	v_fma_f32 v209, v113, v116, v217
	v_fma_f32 v210, v106, v116, v218
	v_fma_f32 v211, v107, v116, v219
	v_fma_f32 v212, v108, v116, v220
	v_fma_f32 v213, v109, v116, v221
	v_exp_f32_e32 v206, v206
	v_exp_f32_e32 v207, v207
	v_exp_f32_e32 v208, v208
	v_exp_f32_e32 v209, v209
	v_exp_f32_e32 v210, v210
	v_exp_f32_e32 v211, v211
	v_exp_f32_e32 v212, v212
	v_exp_f32_e32 v213, v213
	v_add_f32_e32 v206, 1.0, v206
	v_add_f32_e32 v207, 1.0, v207
	v_add_f32_e32 v208, 1.0, v208
	v_add_f32_e32 v209, 1.0, v209
	v_add_f32_e32 v210, 1.0, v210
	v_add_f32_e32 v211, 1.0, v211
	v_add_f32_e32 v212, 1.0, v212
	v_add_f32_e32 v213, 1.0, v213
	v_rcp_f32_e32 v110, v206
	v_rcp_f32_e32 v111, v207
	v_rcp_f32_e32 v112, v208
	v_rcp_f32_e32 v113, v209
	v_rcp_f32_e32 v117, v210
	v_rcp_f32_e32 v118, v211
	v_rcp_f32_e32 v119, v212
	v_rcp_f32_e32 v109, v213
	v_cvt_pk_bf16_f32 v106, v110, v111
	v_cvt_pk_bf16_f32 v107, v112, v113
	v_cvt_pk_bf16_f32 v108, v117, v118
	v_cvt_pk_bf16_f32 v109, v119, v109
	global_store_dwordx4 v[114:115], v[106:109], off nt
	s_nop 1
	v_fma_f32 v206, v102, v116, v238
	v_fma_f32 v207, v103, v116, v239
	v_fma_f32 v208, v104, v116, v240
	v_fma_f32 v209, v105, v116, v241
	v_fma_f32 v210, v98, v116, v242
	v_fma_f32 v211, v99, v116, v243
	v_fma_f32 v212, v100, v116, v244
	v_fma_f32 v213, v101, v116, v245
	v_exp_f32_e32 v206, v206
	v_exp_f32_e32 v207, v207
	v_exp_f32_e32 v208, v208
	v_exp_f32_e32 v209, v209
	v_exp_f32_e32 v210, v210
	v_exp_f32_e32 v211, v211
	v_exp_f32_e32 v212, v212
	v_exp_f32_e32 v213, v213
	v_add_f32_e32 v206, 1.0, v206
	v_add_f32_e32 v207, 1.0, v207
	v_add_f32_e32 v208, 1.0, v208
	v_add_f32_e32 v209, 1.0, v209
	v_add_f32_e32 v210, 1.0, v210
	v_add_f32_e32 v211, 1.0, v211
	v_add_f32_e32 v212, 1.0, v212
	v_add_f32_e32 v213, 1.0, v213
	v_rcp_f32_e32 v102, v206
	v_rcp_f32_e32 v103, v207
	v_rcp_f32_e32 v104, v208
	v_rcp_f32_e32 v105, v209
	v_rcp_f32_e32 v106, v210
	v_rcp_f32_e32 v107, v211
	v_rcp_f32_e32 v108, v212
	v_rcp_f32_e32 v101, v213
	v_cvt_pk_bf16_f32 v98, v102, v103
	v_cvt_pk_bf16_f32 v99, v104, v105
	v_cvt_pk_bf16_f32 v100, v106, v107
	v_cvt_pk_bf16_f32 v101, v108, v101
	global_store_dwordx4 v[114:115], v[98:101], off offset:256 nt
	s_nop 1
	v_fmamk_f32 v98, v175, 0x3a800000, v223
	v_rsq_f32_e32 v100, v98
	s_nop 0
	v_mul_f32_e32 v100, 0xbfb8aa3b, v100
	v_mad_i64_i32 v[98:99], s[0:1], v174, s89, v[156:157]
	v_lshl_add_u64 v[98:99], v[98:99], 0, v[158:159]
	v_fma_f32 v206, v92, v100, v214
	v_fma_f32 v207, v93, v100, v215
	v_fma_f32 v208, v94, v100, v216
	v_fma_f32 v209, v95, v100, v217
	v_fma_f32 v210, v88, v100, v218
	v_fma_f32 v211, v89, v100, v219
	v_fma_f32 v212, v90, v100, v220
	v_fma_f32 v213, v91, v100, v221
	v_exp_f32_e32 v206, v206
	v_exp_f32_e32 v207, v207
	v_exp_f32_e32 v208, v208
	v_exp_f32_e32 v209, v209
	v_exp_f32_e32 v210, v210
	v_exp_f32_e32 v211, v211
	v_exp_f32_e32 v212, v212
	v_exp_f32_e32 v213, v213
	v_add_f32_e32 v206, 1.0, v206
	v_add_f32_e32 v207, 1.0, v207
	v_add_f32_e32 v208, 1.0, v208
	v_add_f32_e32 v209, 1.0, v209
	v_add_f32_e32 v210, 1.0, v210
	v_add_f32_e32 v211, 1.0, v211
	v_add_f32_e32 v212, 1.0, v212
	v_add_f32_e32 v213, 1.0, v213
	v_rcp_f32_e32 v92, v206
	v_rcp_f32_e32 v93, v207
	v_rcp_f32_e32 v94, v208
	v_rcp_f32_e32 v95, v209
	v_rcp_f32_e32 v101, v210
	v_rcp_f32_e32 v102, v211
	v_rcp_f32_e32 v103, v212
	v_rcp_f32_e32 v91, v213
	v_cvt_pk_bf16_f32 v88, v92, v93
	v_cvt_pk_bf16_f32 v89, v94, v95
	v_cvt_pk_bf16_f32 v90, v101, v102
	v_cvt_pk_bf16_f32 v91, v103, v91
	global_store_dwordx4 v[98:99], v[88:91], off nt
	s_nop 1
	v_fma_f32 v206, v84, v100, v238
	v_fma_f32 v207, v85, v100, v239
	v_fma_f32 v208, v86, v100, v240
	v_fma_f32 v209, v87, v100, v241
	v_fma_f32 v210, v80, v100, v242
	v_fma_f32 v211, v81, v100, v243
	v_fma_f32 v212, v82, v100, v244
	v_fma_f32 v213, v83, v100, v245
	v_exp_f32_e32 v206, v206
	v_exp_f32_e32 v207, v207
	v_exp_f32_e32 v208, v208
	v_exp_f32_e32 v209, v209
	v_exp_f32_e32 v210, v210
	v_exp_f32_e32 v211, v211
	v_exp_f32_e32 v212, v212
	v_exp_f32_e32 v213, v213
	v_add_f32_e32 v206, 1.0, v206
	v_add_f32_e32 v207, 1.0, v207
	v_add_f32_e32 v208, 1.0, v208
	v_add_f32_e32 v209, 1.0, v209
	v_add_f32_e32 v210, 1.0, v210
	v_add_f32_e32 v211, 1.0, v211
	v_add_f32_e32 v212, 1.0, v212
	v_add_f32_e32 v213, 1.0, v213
	v_rcp_f32_e32 v84, v206
	v_rcp_f32_e32 v85, v207
	v_rcp_f32_e32 v86, v208
; __device__ __forceinline__ u32x4 pack8(const float* f) { u32x4 w; w.x = cvt_pk_bf16(f[0], f[1]); w.y = cvt_pk_bf16(f[2], f[3]); w.z = cvt_pk_bf16(f[4], f[5]); w.w = cvt_pk_bf16(f[6], f[7]); return w; }
;     __device__ __forceinline__ void operator()(AccT& acc, const Unit& u, int wr, int wc, int fr, int fq) const {
;     ...
;         for (int ai = 0; ai < 2; ++ai)
; #pragma unroll
;             for (int m = 0; m < 4; ++m) {
;                 const int row = u.pm * 256 + ai * 128 + wr * 64 + m * 16 + fr;
;                 const float rs = __builtin_amdgcn_rsqf(rsv[ai][m] * (1.0f / 1024.0f) + EPS);
;                 bf16_t* rowp = P + (size_t)row * INW + col0;
; #pragma unroll
;                 for (int bj = 0; bj < 2; ++bj) {
;                     float v[8];
; #pragma unroll
;                     for (int n = 0; n < 2; ++n)
; #pragma unroll
;                         for (int j = 0; j < 4; ++j) {
;                             float x = acc[ai][bj][m][n][j] * rs;
;                             if (gate) { x += gb[bj][n][j]; x = __builtin_amdgcn_rcpf(1.0f + __builtin_amdgcn_exp2f(-LOG2E * x)); }
;                             v[n * 4 + j] = x;
;                         }
;                     *(u32x4*)(rowp + bj * 128) = pack8(v);
;                 }
	v_rcp_f32_e32 v87, v209
	v_rcp_f32_e32 v88, v210
	v_rcp_f32_e32 v89, v211
	v_rcp_f32_e32 v90, v212
	v_rcp_f32_e32 v83, v213
	v_cvt_pk_bf16_f32 v80, v84, v85
	v_cvt_pk_bf16_f32 v81, v86, v87
	v_cvt_pk_bf16_f32 v82, v88, v89
	v_cvt_pk_bf16_f32 v83, v90, v83
	global_store_dwordx4 v[98:99], v[80:83], off offset:256 nt
	s_nop 1
	v_fmamk_f32 v80, v173, 0x3a800000, v223
	v_rsq_f32_e32 v82, v80
	s_nop 0
	v_mul_f32_e32 v82, 0xbfb8aa3b, v82
	v_mad_i64_i32 v[80:81], s[0:1], v172, s89, v[156:157]
	v_lshl_add_u64 v[80:81], v[80:81], 0, v[158:159]
	v_fma_f32 v206, v76, v82, v214
	v_fma_f32 v207, v77, v82, v215
	v_fma_f32 v208, v78, v82, v216
	v_fma_f32 v209, v79, v82, v217
	v_fma_f32 v210, v72, v82, v218
	v_fma_f32 v211, v73, v82, v219
	v_fma_f32 v212, v74, v82, v220
	v_fma_f32 v213, v75, v82, v221
	v_exp_f32_e32 v206, v206
	v_exp_f32_e32 v207, v207
	v_exp_f32_e32 v208, v208
	v_exp_f32_e32 v209, v209
	v_exp_f32_e32 v210, v210
	v_exp_f32_e32 v211, v211
	v_exp_f32_e32 v212, v212
	v_exp_f32_e32 v213, v213
	v_add_f32_e32 v206, 1.0, v206
	v_add_f32_e32 v207, 1.0, v207
	v_add_f32_e32 v208, 1.0, v208
	v_add_f32_e32 v209, 1.0, v209
	v_add_f32_e32 v210, 1.0, v210
	v_add_f32_e32 v211, 1.0, v211
	v_add_f32_e32 v212, 1.0, v212
	v_add_f32_e32 v213, 1.0, v213
	v_rcp_f32_e32 v76, v206
	v_rcp_f32_e32 v77, v207
	v_rcp_f32_e32 v78, v208
	v_rcp_f32_e32 v79, v209
	v_rcp_f32_e32 v83, v210
	v_rcp_f32_e32 v84, v211
	v_rcp_f32_e32 v85, v212
	v_rcp_f32_e32 v75, v213
	v_cvt_pk_bf16_f32 v72, v76, v77
	v_cvt_pk_bf16_f32 v73, v78, v79
	v_cvt_pk_bf16_f32 v74, v83, v84
	v_cvt_pk_bf16_f32 v75, v85, v75
	global_store_dwordx4 v[80:81], v[72:75], off nt
	s_nop 1
	v_fma_f32 v206, v68, v82, v238
	v_fma_f32 v207, v69, v82, v239
	v_fma_f32 v208, v70, v82, v240
	v_fma_f32 v209, v71, v82, v241
	v_fma_f32 v210, v64, v82, v242
	v_fma_f32 v211, v65, v82, v243
	v_fma_f32 v212, v66, v82, v244
	v_fma_f32 v213, v67, v82, v245
	v_exp_f32_e32 v206, v206
	v_exp_f32_e32 v207, v207
	v_exp_f32_e32 v208, v208
	v_exp_f32_e32 v209, v209
	v_exp_f32_e32 v210, v210
	v_exp_f32_e32 v211, v211
	v_exp_f32_e32 v212, v212
	v_exp_f32_e32 v213, v213
	v_add_f32_e32 v206, 1.0, v206
	v_add_f32_e32 v207, 1.0, v207
	v_add_f32_e32 v208, 1.0, v208
	v_add_f32_e32 v209, 1.0, v209
	v_add_f32_e32 v210, 1.0, v210
	v_add_f32_e32 v211, 1.0, v211
	v_add_f32_e32 v212, 1.0, v212
	v_add_f32_e32 v213, 1.0, v213
	v_rcp_f32_e32 v68, v206
	v_rcp_f32_e32 v69, v207
	v_rcp_f32_e32 v70, v208
	v_rcp_f32_e32 v71, v209
	v_rcp_f32_e32 v72, v210
	v_rcp_f32_e32 v73, v211
	v_rcp_f32_e32 v74, v212
	v_rcp_f32_e32 v67, v213
	v_cvt_pk_bf16_f32 v64, v68, v69
	v_cvt_pk_bf16_f32 v65, v70, v71
	v_cvt_pk_bf16_f32 v66, v72, v73
	v_cvt_pk_bf16_f32 v67, v74, v67
	global_store_dwordx4 v[80:81], v[64:67], off offset:256 nt
	s_nop 1
	v_fmamk_f32 v64, v171, 0x3a800000, v223
	v_rsq_f32_e32 v66, v64
	s_nop 0
	v_mul_f32_e32 v66, 0xbfb8aa3b, v66
	v_mad_i64_i32 v[64:65], s[0:1], v170, s89, v[156:157]
	v_lshl_add_u64 v[64:65], v[64:65], 0, v[158:159]
	v_fma_f32 v206, v60, v66, v214
	v_fma_f32 v207, v61, v66, v215
	v_fma_f32 v208, v62, v66, v216
	v_fma_f32 v209, v63, v66, v217
	v_fma_f32 v210, v56, v66, v218
	v_fma_f32 v211, v57, v66, v219
	v_fma_f32 v212, v58, v66, v220
	v_fma_f32 v213, v59, v66, v221
	v_exp_f32_e32 v206, v206
	v_exp_f32_e32 v207, v207
	v_exp_f32_e32 v208, v208
	v_exp_f32_e32 v209, v209
	v_exp_f32_e32 v210, v210
	v_exp_f32_e32 v211, v211
	v_exp_f32_e32 v212, v212
	v_exp_f32_e32 v213, v213
	v_add_f32_e32 v206, 1.0, v206
	v_add_f32_e32 v207, 1.0, v207
	v_add_f32_e32 v208, 1.0, v208
	v_add_f32_e32 v209, 1.0, v209
	v_add_f32_e32 v210, 1.0, v210
	v_add_f32_e32 v211, 1.0, v211
	v_add_f32_e32 v212, 1.0, v212
	v_add_f32_e32 v213, 1.0, v213
	v_rcp_f32_e32 v60, v206
	v_rcp_f32_e32 v61, v207
	v_rcp_f32_e32 v62, v208
	v_rcp_f32_e32 v63, v209
	v_rcp_f32_e32 v67, v210
	v_rcp_f32_e32 v68, v211
	v_rcp_f32_e32 v69, v212
	v_rcp_f32_e32 v59, v213
	v_cvt_pk_bf16_f32 v56, v60, v61
	v_cvt_pk_bf16_f32 v57, v62, v63
	v_cvt_pk_bf16_f32 v58, v67, v68
	v_cvt_pk_bf16_f32 v59, v69, v59
	global_store_dwordx4 v[64:65], v[56:59], off nt
	s_nop 1
	v_fma_f32 v206, v48, v66, v238
	v_fma_f32 v207, v49, v66, v239
	v_fma_f32 v208, v50, v66, v240
	v_fma_f32 v209, v51, v66, v241
	v_fma_f32 v210, v36, v66, v242
	v_fma_f32 v211, v37, v66, v243
	v_fma_f32 v212, v38, v66, v244
	v_fma_f32 v213, v39, v66, v245
	v_exp_f32_e32 v206, v206
	v_exp_f32_e32 v207, v207
	v_exp_f32_e32 v208, v208
	v_exp_f32_e32 v209, v209
	v_exp_f32_e32 v210, v210
	v_exp_f32_e32 v211, v211
	v_exp_f32_e32 v212, v212
	v_exp_f32_e32 v213, v213
	v_add_f32_e32 v206, 1.0, v206
	v_add_f32_e32 v207, 1.0, v207
	v_add_f32_e32 v208, 1.0, v208
	v_add_f32_e32 v209, 1.0, v209
	v_add_f32_e32 v210, 1.0, v210
	v_add_f32_e32 v211, 1.0, v211
	v_add_f32_e32 v212, 1.0, v212
	v_add_f32_e32 v213, 1.0, v213
	v_rcp_f32_e32 v48, v206
	v_rcp_f32_e32 v49, v207
	v_rcp_f32_e32 v50, v208
	v_rcp_f32_e32 v51, v209
	v_rcp_f32_e32 v56, v210
	v_rcp_f32_e32 v57, v211
	v_rcp_f32_e32 v58, v212
	v_rcp_f32_e32 v39, v213
	v_cvt_pk_bf16_f32 v36, v48, v49
	v_cvt_pk_bf16_f32 v37, v50, v51
	v_cvt_pk_bf16_f32 v38, v56, v57
	v_cvt_pk_bf16_f32 v39, v58, v39
	global_store_dwordx4 v[64:65], v[36:39], off offset:256 nt
	s_nop 1
	v_fmamk_f32 v36, v169, 0x3a800000, v223
	v_rsq_f32_e32 v38, v36
	s_nop 0
	v_mul_f32_e32 v38, 0xbfb8aa3b, v38
	v_mad_i64_i32 v[36:37], s[0:1], v168, s89, v[156:157]
	v_lshl_add_u64 v[36:37], v[36:37], 0, v[158:159]
	v_fma_f32 v206, v28, v38, v214
	v_fma_f32 v207, v29, v38, v215
	v_fma_f32 v208, v30, v38, v216
	v_fma_f32 v209, v31, v38, v217
	v_fma_f32 v210, v24, v38, v218
	v_fma_f32 v211, v25, v38, v219
	v_fma_f32 v212, v26, v38, v220
; __device__ __forceinline__ u32x4 pack8(const float* f) { u32x4 w; w.x = cvt_pk_bf16(f[0], f[1]); w.y = cvt_pk_bf16(f[2], f[3]); w.z = cvt_pk_bf16(f[4], f[5]); w.w = cvt_pk_bf16(f[6], f[7]); return w; }
;     __device__ __forceinline__ void operator()(AccT& acc, const Unit& u, int wr, int wc, int fr, int fq) const {
;     ...
;         for (int ai = 0; ai < 2; ++ai)
; #pragma unroll
;             for (int m = 0; m < 4; ++m) {
;                 const int row = u.pm * 256 + ai * 128 + wr * 64 + m * 16 + fr;
;                 const float rs = __builtin_amdgcn_rsqf(rsv[ai][m] * (1.0f / 1024.0f) + EPS);
;                 bf16_t* rowp = P + (size_t)row * INW + col0;
; #pragma unroll
;                 for (int bj = 0; bj < 2; ++bj) {
;                     float v[8];
; #pragma unroll
;                     for (int n = 0; n < 2; ++n)
; #pragma unroll
;                         for (int j = 0; j < 4; ++j) {
;                             float x = acc[ai][bj][m][n][j] * rs;
;                             if (gate) { x += gb[bj][n][j]; x = __builtin_amdgcn_rcpf(1.0f + __builtin_amdgcn_exp2f(-LOG2E * x)); }
;                             v[n * 4 + j] = x;
;                         }
;                     *(u32x4*)(rowp + bj * 128) = pack8(v);
;                 }
	v_fma_f32 v213, v27, v38, v221
	v_exp_f32_e32 v206, v206
	v_exp_f32_e32 v207, v207
	v_exp_f32_e32 v208, v208
	v_exp_f32_e32 v209, v209
	v_exp_f32_e32 v210, v210
	v_exp_f32_e32 v211, v211
	v_exp_f32_e32 v212, v212
	v_exp_f32_e32 v213, v213
	v_add_f32_e32 v206, 1.0, v206
	v_add_f32_e32 v207, 1.0, v207
	v_add_f32_e32 v208, 1.0, v208
	v_add_f32_e32 v209, 1.0, v209
	v_add_f32_e32 v210, 1.0, v210
	v_add_f32_e32 v211, 1.0, v211
	v_add_f32_e32 v212, 1.0, v212
	v_add_f32_e32 v213, 1.0, v213
	v_rcp_f32_e32 v28, v206
	v_rcp_f32_e32 v29, v207
	v_rcp_f32_e32 v30, v208
	v_rcp_f32_e32 v31, v209
	v_rcp_f32_e32 v39, v210
	v_rcp_f32_e32 v48, v211
	v_rcp_f32_e32 v49, v212
	v_rcp_f32_e32 v27, v213
	v_cvt_pk_bf16_f32 v24, v28, v29
	v_cvt_pk_bf16_f32 v25, v30, v31
	v_cvt_pk_bf16_f32 v26, v39, v48
	v_cvt_pk_bf16_f32 v27, v49, v27
	global_store_dwordx4 v[36:37], v[24:27], off nt
	s_nop 1
	v_fma_f32 v206, v20, v38, v238
	v_fma_f32 v207, v21, v38, v239
	v_fma_f32 v208, v22, v38, v240
	v_fma_f32 v209, v23, v38, v241
	v_fma_f32 v210, v16, v38, v242
	v_fma_f32 v211, v17, v38, v243
	v_fma_f32 v212, v18, v38, v244
	v_fma_f32 v213, v19, v38, v245
	v_exp_f32_e32 v206, v206
	v_exp_f32_e32 v207, v207
	v_exp_f32_e32 v208, v208
	v_exp_f32_e32 v209, v209
	v_exp_f32_e32 v210, v210
	v_exp_f32_e32 v211, v211
	v_exp_f32_e32 v212, v212
	v_exp_f32_e32 v213, v213
	v_add_f32_e32 v206, 1.0, v206
	v_add_f32_e32 v207, 1.0, v207
	v_add_f32_e32 v208, 1.0, v208
	v_add_f32_e32 v209, 1.0, v209
	v_add_f32_e32 v210, 1.0, v210
	v_add_f32_e32 v211, 1.0, v211
	v_add_f32_e32 v212, 1.0, v212
	v_add_f32_e32 v213, 1.0, v213
	v_rcp_f32_e32 v20, v206
	v_rcp_f32_e32 v21, v207
	v_rcp_f32_e32 v22, v208
	v_rcp_f32_e32 v23, v209
	v_rcp_f32_e32 v24, v210
	v_rcp_f32_e32 v25, v211
	v_rcp_f32_e32 v26, v212
	v_rcp_f32_e32 v19, v213
	v_cvt_pk_bf16_f32 v16, v20, v21
	v_cvt_pk_bf16_f32 v17, v22, v23
	v_cvt_pk_bf16_f32 v18, v24, v25
	v_cvt_pk_bf16_f32 v19, v26, v19
	global_store_dwordx4 v[36:37], v[16:19], off offset:256 nt
	s_nop 1
	v_fmamk_f32 v16, v167, 0x3a800000, v223
	v_rsq_f32_e32 v18, v16
	v_mad_i64_i32 v[16:17], s[0:1], v166, s89, v[156:157]
	v_lshl_add_u64 v[16:17], v[16:17], 0, v[158:159]
	v_fmac_f32_e32 v52, v12, v18
	v_mul_f32_e32 v19, v12, v18
	v_mul_f32_e32 v12, 0xbfb8aa3b, v52
	v_exp_f32_e32 v12, v12
	v_fmac_f32_e32 v53, v13, v18
	v_fmac_f32_e32 v54, v14, v18
	v_fmac_f32_e32 v55, v15, v18
	v_add_f32_e32 v12, 1.0, v12
	v_rcp_f32_e32 v12, v12
	v_fmac_f32_e32 v44, v8, v18
	v_fmac_f32_e32 v45, v9, v18
	v_fmac_f32_e32 v46, v10, v18
	v_cndmask_b32_e64 v12, v19, v12, s[42:43]
	v_mul_f32_e32 v19, v13, v18
	v_mul_f32_e32 v13, 0xbfb8aa3b, v53
	v_exp_f32_e32 v13, v13
	v_fmac_f32_e32 v47, v11, v18
	v_fmac_f32_e32 v40, v4, v18
	v_fmac_f32_e32 v41, v5, v18
	v_add_f32_e32 v13, 1.0, v13
	v_rcp_f32_e32 v13, v13
	v_fmac_f32_e32 v42, v6, v18
	v_fmac_f32_e32 v43, v7, v18
	v_fmac_f32_e32 v32, v0, v18
	v_cndmask_b32_e64 v13, v19, v13, s[42:43]
	v_mul_f32_e32 v19, v14, v18
	v_mul_f32_e32 v14, 0xbfb8aa3b, v54
	v_exp_f32_e32 v14, v14
	v_fmac_f32_e32 v33, v1, v18
	v_fmac_f32_e32 v34, v2, v18
	v_fmac_f32_e32 v35, v3, v18
	v_add_f32_e32 v14, 1.0, v14
	v_rcp_f32_e32 v14, v14
	s_mov_b64 s[0:1], -1
	v_cndmask_b32_e64 v14, v19, v14, s[42:43]
	v_mul_f32_e32 v19, v15, v18
	v_mul_f32_e32 v15, 0xbfb8aa3b, v55
	v_exp_f32_e32 v15, v15
	s_nop 0
	v_add_f32_e32 v15, 1.0, v15
	v_rcp_f32_e32 v15, v15
	s_nop 0
	v_cndmask_b32_e64 v15, v19, v15, s[42:43]
	v_mul_f32_e32 v19, v8, v18
	v_mul_f32_e32 v8, 0xbfb8aa3b, v44
	v_exp_f32_e32 v8, v8
	s_nop 0
	v_add_f32_e32 v8, 1.0, v8
	v_rcp_f32_e32 v8, v8
	s_nop 0
	v_cndmask_b32_e64 v19, v19, v8, s[42:43]
	v_mul_f32_e32 v8, v9, v18
	v_mul_f32_e32 v9, 0xbfb8aa3b, v45
	v_exp_f32_e32 v9, v9
	s_nop 0
	v_add_f32_e32 v9, 1.0, v9
	v_rcp_f32_e32 v9, v9
	s_nop 0
	v_cndmask_b32_e64 v20, v8, v9, s[42:43]
	v_mul_f32_e32 v9, 0xbfb8aa3b, v46
	v_exp_f32_e32 v9, v9
	v_mul_f32_e32 v8, v10, v18
	v_add_f32_e32 v9, 1.0, v9
	v_rcp_f32_e32 v9, v9
	s_nop 0
	v_cndmask_b32_e64 v21, v8, v9, s[42:43]
	v_mul_f32_e32 v9, 0xbfb8aa3b, v47
	v_exp_f32_e32 v9, v9
	v_mul_f32_e32 v8, v11, v18
	v_add_f32_e32 v9, 1.0, v9
	v_rcp_f32_e32 v9, v9
	s_nop 0
	v_cndmask_b32_e64 v11, v8, v9, s[42:43]
	v_cvt_pk_bf16_f32 v8, v12, v13
	v_cvt_pk_bf16_f32 v9, v14, v15
	v_cvt_pk_bf16_f32 v10, v19, v20
	v_cvt_pk_bf16_f32 v11, v21, v11
	global_store_dwordx4 v[16:17], v[8:11], off nt
	s_nop 1
	v_mul_f32_e32 v8, v4, v18
	v_mul_f32_e32 v4, 0xbfb8aa3b, v40
	v_exp_f32_e32 v4, v4
	s_nop 0
	v_add_f32_e32 v4, 1.0, v4
	v_rcp_f32_e32 v4, v4
	s_nop 0
	v_cndmask_b32_e64 v4, v8, v4, s[42:43]
	v_mul_f32_e32 v8, v5, v18
	v_mul_f32_e32 v5, 0xbfb8aa3b, v41
	v_exp_f32_e32 v5, v5
	s_nop 0
	v_add_f32_e32 v5, 1.0, v5
	v_rcp_f32_e32 v5, v5
	s_nop 0
	v_cndmask_b32_e64 v5, v8, v5, s[42:43]
	v_mul_f32_e32 v8, v6, v18
	v_mul_f32_e32 v6, 0xbfb8aa3b, v42
	v_exp_f32_e32 v6, v6
	s_nop 0
	v_add_f32_e32 v6, 1.0, v6
	v_rcp_f32_e32 v6, v6
	s_nop 0
	v_cndmask_b32_e64 v6, v8, v6, s[42:43]
	v_mul_f32_e32 v8, v7, v18
	v_mul_f32_e32 v7, 0xbfb8aa3b, v43
	v_exp_f32_e32 v7, v7
	s_nop 0
	v_add_f32_e32 v7, 1.0, v7
	v_rcp_f32_e32 v7, v7
	s_nop 0
	v_cndmask_b32_e64 v7, v8, v7, s[42:43]
	v_mul_f32_e32 v8, v0, v18
	v_mul_f32_e32 v0, 0xbfb8aa3b, v32
	v_exp_f32_e32 v0, v0
	s_nop 0
	v_add_f32_e32 v0, 1.0, v0
	v_rcp_f32_e32 v0, v0
	s_nop 0
	v_cndmask_b32_e64 v8, v8, v0, s[42:43]
	v_mul_f32_e32 v0, v1, v18
	v_mul_f32_e32 v1, 0xbfb8aa3b, v33
	v_exp_f32_e32 v1, v1
	s_nop 0
	v_add_f32_e32 v1, 1.0, v1
	v_rcp_f32_e32 v1, v1
	s_nop 0
	v_cndmask_b32_e64 v9, v0, v1, s[42:43]
	v_mul_f32_e32 v1, 0xbfb8aa3b, v34
	v_exp_f32_e32 v1, v1
	v_mul_f32_e32 v0, v2, v18
	v_add_f32_e32 v1, 1.0, v1
	v_rcp_f32_e32 v1, v1
	s_nop 0
	v_cndmask_b32_e64 v10, v0, v1, s[42:43]
	v_mul_f32_e32 v1, 0xbfb8aa3b, v35
	v_exp_f32_e32 v1, v1
	v_mul_f32_e32 v0, v3, v18
	v_add_f32_e32 v1, 1.0, v1
	v_rcp_f32_e32 v1, v1
	s_nop 0
	v_cndmask_b32_e64 v3, v0, v1, s[42:43]
	v_cvt_pk_bf16_f32 v0, v4, v5
	v_cvt_pk_bf16_f32 v1, v6, v7
	v_cvt_pk_bf16_f32 v2, v8, v9
	v_cvt_pk_bf16_f32 v3, v10, v3
	global_store_dwordx4 v[16:17], v[0:3], off offset:256 nt
	s_branch .Lmy_p1_join
; __device__ __forceinline__ u32x4 pack8(const float* f) { u32x4 w; w.x = cvt_pk_bf16(f[0], f[1]); w.y = cvt_pk_bf16(f[2], f[3]); w.z = cvt_pk_bf16(f[4], f[5]); w.w = cvt_pk_bf16(f[6], f[7]); return w; }
;     __device__ __forceinline__ void operator()(AccT& acc, const Unit& u, int wr, int wc, int fr, int fq) const {
;     ...
;         for (int ai = 0; ai < 2; ++ai)
; #pragma unroll
;             for (int m = 0; m < 4; ++m) {
;                 const int row = u.pm * 256 + ai * 128 + wr * 64 + m * 16 + fr;
;                 const float rs = __builtin_amdgcn_rsqf(rsv[ai][m] * (1.0f / 1024.0f) + EPS);
;                 bf16_t* rowp = P + (size_t)row * INW + col0;
; #pragma unroll
;                 for (int bj = 0; bj < 2; ++bj) {
;                     float v[8];
; #pragma unroll
;                     for (int n = 0; n < 2; ++n)
; #pragma unroll
;                         for (int j = 0; j < 4; ++j) {
;                             float x = acc[ai][bj][m][n][j] * rs;
;                             if (gate) { x += gb[bj][n][j]; x = __builtin_amdgcn_rcpf(1.0f + __builtin_amdgcn_exp2f(-LOG2E * x)); }
;                             v[n * 4 + j] = x;
;                         }
;                     *(u32x4*)(rowp + bj * 128) = pack8(v);
;                 }
.Lmy_p1_nongate:
	v_fmamk_f32 v156, v161, 0x3a800000, v223
	v_rsq_f32_e32 v180, v156
	v_mov_b64_e32 v[156:157], s[84:85]
	v_mad_i64_i32 v[160:161], s[0:1], v160, s89, v[156:157]
	v_lshl_add_u64 v[160:161], v[160:161], 0, v[158:159]
	v_mul_f32_e32 v142, v142, v180
	v_mul_f32_e32 v143, v143, v180
	v_mul_f32_e32 v144, v144, v180
	v_mul_f32_e32 v145, v145, v180
	v_mul_f32_e32 v181, v138, v180
	v_mul_f32_e32 v182, v139, v180
	v_mul_f32_e32 v183, v140, v180
	v_mul_f32_e32 v141, v141, v180
	v_cvt_pk_bf16_f32 v138, v142, v143
	v_cvt_pk_bf16_f32 v139, v144, v145
	v_cvt_pk_bf16_f32 v140, v181, v182
	v_cvt_pk_bf16_f32 v141, v183, v141
	global_store_dwordx4 v[160:161], v[138:141], off nt
	s_nop 1
	v_mul_f32_e32 v134, v134, v180
	v_mul_f32_e32 v135, v135, v180
	v_mul_f32_e32 v136, v136, v180
	v_mul_f32_e32 v137, v137, v180
	v_mul_f32_e32 v138, v130, v180
	v_mul_f32_e32 v139, v131, v180
	v_mul_f32_e32 v140, v132, v180
	v_mul_f32_e32 v133, v133, v180
	v_cvt_pk_bf16_f32 v130, v134, v135
	v_cvt_pk_bf16_f32 v131, v136, v137
	v_cvt_pk_bf16_f32 v132, v138, v139
	v_cvt_pk_bf16_f32 v133, v140, v133
	global_store_dwordx4 v[160:161], v[130:133], off offset:256 nt
	s_nop 1
	v_fmamk_f32 v130, v179, 0x3a800000, v223
	v_rsq_f32_e32 v132, v130
	v_mad_i64_i32 v[130:131], s[0:1], v178, s89, v[156:157]
	v_lshl_add_u64 v[130:131], v[130:131], 0, v[158:159]
	v_mul_f32_e32 v126, v126, v132
	v_mul_f32_e32 v127, v127, v132
	v_mul_f32_e32 v128, v128, v132
	v_mul_f32_e32 v129, v129, v132
	v_mul_f32_e32 v133, v122, v132
	v_mul_f32_e32 v134, v123, v132
	v_mul_f32_e32 v135, v124, v132
	v_mul_f32_e32 v125, v125, v132
	v_cvt_pk_bf16_f32 v122, v126, v127
	v_cvt_pk_bf16_f32 v123, v128, v129
	v_cvt_pk_bf16_f32 v124, v133, v134
	v_cvt_pk_bf16_f32 v125, v135, v125
	global_store_dwordx4 v[130:131], v[122:125], off nt
	s_nop 1
	v_mul_f32_e32 v118, v118, v132
	v_mul_f32_e32 v119, v119, v132
	v_mul_f32_e32 v120, v120, v132
	v_mul_f32_e32 v121, v121, v132
	v_mul_f32_e32 v122, v114, v132
	v_mul_f32_e32 v123, v115, v132
	v_mul_f32_e32 v124, v116, v132
	v_mul_f32_e32 v117, v117, v132
	v_cvt_pk_bf16_f32 v114, v118, v119
	v_cvt_pk_bf16_f32 v115, v120, v121
	v_cvt_pk_bf16_f32 v116, v122, v123
	v_cvt_pk_bf16_f32 v117, v124, v117
	global_store_dwordx4 v[130:131], v[114:117], off offset:256 nt
	s_nop 1
	v_fmamk_f32 v114, v177, 0x3a800000, v223
	v_rsq_f32_e32 v116, v114
	v_mad_i64_i32 v[114:115], s[0:1], v176, s89, v[156:157]
	v_lshl_add_u64 v[114:115], v[114:115], 0, v[158:159]
	v_mul_f32_e32 v110, v110, v116
	v_mul_f32_e32 v111, v111, v116
	v_mul_f32_e32 v112, v112, v116
	v_mul_f32_e32 v113, v113, v116
	v_mul_f32_e32 v117, v106, v116
	v_mul_f32_e32 v118, v107, v116
	v_mul_f32_e32 v119, v108, v116
	v_mul_f32_e32 v109, v109, v116
	v_cvt_pk_bf16_f32 v106, v110, v111
	v_cvt_pk_bf16_f32 v107, v112, v113
	v_cvt_pk_bf16_f32 v108, v117, v118
	v_cvt_pk_bf16_f32 v109, v119, v109
	global_store_dwordx4 v[114:115], v[106:109], off nt
	s_nop 1
	v_mul_f32_e32 v102, v102, v116
	v_mul_f32_e32 v103, v103, v116
	v_mul_f32_e32 v104, v104, v116
	v_mul_f32_e32 v105, v105, v116
	v_mul_f32_e32 v106, v98, v116
	v_mul_f32_e32 v107, v99, v116
	v_mul_f32_e32 v108, v100, v116
	v_mul_f32_e32 v101, v101, v116
	v_cvt_pk_bf16_f32 v98, v102, v103
	v_cvt_pk_bf16_f32 v99, v104, v105
	v_cvt_pk_bf16_f32 v100, v106, v107
	v_cvt_pk_bf16_f32 v101, v108, v101
	global_store_dwordx4 v[114:115], v[98:101], off offset:256 nt
	s_nop 1
	v_fmamk_f32 v98, v175, 0x3a800000, v223
	v_rsq_f32_e32 v100, v98
	v_mad_i64_i32 v[98:99], s[0:1], v174, s89, v[156:157]
	v_lshl_add_u64 v[98:99], v[98:99], 0, v[158:159]
	v_mul_f32_e32 v92, v92, v100
	v_mul_f32_e32 v93, v93, v100
	v_mul_f32_e32 v94, v94, v100
	v_mul_f32_e32 v95, v95, v100
	v_mul_f32_e32 v101, v88, v100
	v_mul_f32_e32 v102, v89, v100
	v_mul_f32_e32 v103, v90, v100
	v_mul_f32_e32 v91, v91, v100
	v_cvt_pk_bf16_f32 v88, v92, v93
	v_cvt_pk_bf16_f32 v89, v94, v95
	v_cvt_pk_bf16_f32 v90, v101, v102
	v_cvt_pk_bf16_f32 v91, v103, v91
	global_store_dwordx4 v[98:99], v[88:91], off nt
	s_nop 1
	v_mul_f32_e32 v84, v84, v100
	v_mul_f32_e32 v85, v85, v100
	v_mul_f32_e32 v86, v86, v100
	v_mul_f32_e32 v87, v87, v100
	v_mul_f32_e32 v88, v80, v100
	v_mul_f32_e32 v89, v81, v100
	v_mul_f32_e32 v90, v82, v100
	v_mul_f32_e32 v83, v83, v100
	v_cvt_pk_bf16_f32 v80, v84, v85
	v_cvt_pk_bf16_f32 v81, v86, v87
	v_cvt_pk_bf16_f32 v82, v88, v89
	v_cvt_pk_bf16_f32 v83, v90, v83
	global_store_dwordx4 v[98:99], v[80:83], off offset:256 nt
	s_nop 1
	v_fmamk_f32 v80, v173, 0x3a800000, v223
	v_rsq_f32_e32 v82, v80
	v_mad_i64_i32 v[80:81], s[0:1], v172, s89, v[156:157]
	v_lshl_add_u64 v[80:81], v[80:81], 0, v[158:159]
	v_mul_f32_e32 v76, v76, v82
	v_mul_f32_e32 v77, v77, v82
	v_mul_f32_e32 v78, v78, v82
	v_mul_f32_e32 v79, v79, v82
	v_mul_f32_e32 v83, v72, v82
	v_mul_f32_e32 v84, v73, v82
	v_mul_f32_e32 v85, v74, v82
	v_mul_f32_e32 v75, v75, v82
	v_cvt_pk_bf16_f32 v72, v76, v77
	v_cvt_pk_bf16_f32 v73, v78, v79
	v_cvt_pk_bf16_f32 v74, v83, v84
	v_cvt_pk_bf16_f32 v75, v85, v75
	global_store_dwordx4 v[80:81], v[72:75], off nt
	s_nop 1
	v_mul_f32_e32 v68, v68, v82
	v_mul_f32_e32 v69, v69, v82
	v_mul_f32_e32 v70, v70, v82
	v_mul_f32_e32 v71, v71, v82
	v_mul_f32_e32 v72, v64, v82
	v_mul_f32_e32 v73, v65, v82
	v_mul_f32_e32 v74, v66, v82
	v_mul_f32_e32 v67, v67, v82
	v_cvt_pk_bf16_f32 v64, v68, v69
	v_cvt_pk_bf16_f32 v65, v70, v71
	v_cvt_pk_bf16_f32 v66, v72, v73
	v_cvt_pk_bf16_f32 v67, v74, v67
	global_store_dwordx4 v[80:81], v[64:67], off offset:256 nt
	s_nop 1
	v_fmamk_f32 v64, v171, 0x3a800000, v223
	v_rsq_f32_e32 v66, v64
	v_mad_i64_i32 v[64:65], s[0:1], v170, s89, v[156:157]
	v_lshl_add_u64 v[64:65], v[64:65], 0, v[158:159]
; __device__ __forceinline__ u32x4 pack8(const float* f) { u32x4 w; w.x = cvt_pk_bf16(f[0], f[1]); w.y = cvt_pk_bf16(f[2], f[3]); w.z = cvt_pk_bf16(f[4], f[5]); w.w = cvt_pk_bf16(f[6], f[7]); return w; }
;     __device__ __forceinline__ void operator()(AccT& acc, const Unit& u, int wr, int wc, int fr, int fq) const {
;     ...
;         for (int ai = 0; ai < 2; ++ai)
; #pragma unroll
;             for (int m = 0; m < 4; ++m) {
;                 const int row = u.pm * 256 + ai * 128 + wr * 64 + m * 16 + fr;
;                 const float rs = __builtin_amdgcn_rsqf(rsv[ai][m] * (1.0f / 1024.0f) + EPS);
;                 bf16_t* rowp = P + (size_t)row * INW + col0;
; #pragma unroll
;                 for (int bj = 0; bj < 2; ++bj) {
;                     float v[8];
; #pragma unroll
;                     for (int n = 0; n < 2; ++n)
; #pragma unroll
;                         for (int j = 0; j < 4; ++j) {
;                             float x = acc[ai][bj][m][n][j] * rs;
;                             if (gate) { x += gb[bj][n][j]; x = __builtin_amdgcn_rcpf(1.0f + __builtin_amdgcn_exp2f(-LOG2E * x)); }
;                             v[n * 4 + j] = x;
;                         }
;                     *(u32x4*)(rowp + bj * 128) = pack8(v);
;                 }
	v_mul_f32_e32 v60, v60, v66
	v_mul_f32_e32 v61, v61, v66
	v_mul_f32_e32 v62, v62, v66
	v_mul_f32_e32 v63, v63, v66
	v_mul_f32_e32 v67, v56, v66
	v_mul_f32_e32 v68, v57, v66
	v_mul_f32_e32 v69, v58, v66
	v_mul_f32_e32 v59, v59, v66
	v_cvt_pk_bf16_f32 v56, v60, v61
	v_cvt_pk_bf16_f32 v57, v62, v63
	v_cvt_pk_bf16_f32 v58, v67, v68
	v_cvt_pk_bf16_f32 v59, v69, v59
	global_store_dwordx4 v[64:65], v[56:59], off nt
	s_nop 1
	v_mul_f32_e32 v48, v48, v66
	v_mul_f32_e32 v49, v49, v66
	v_mul_f32_e32 v50, v50, v66
	v_mul_f32_e32 v51, v51, v66
	v_mul_f32_e32 v56, v36, v66
	v_mul_f32_e32 v57, v37, v66
	v_mul_f32_e32 v58, v38, v66
	v_mul_f32_e32 v39, v39, v66
	v_cvt_pk_bf16_f32 v36, v48, v49
	v_cvt_pk_bf16_f32 v37, v50, v51
	v_cvt_pk_bf16_f32 v38, v56, v57
	v_cvt_pk_bf16_f32 v39, v58, v39
	global_store_dwordx4 v[64:65], v[36:39], off offset:256 nt
	s_nop 1
	v_fmamk_f32 v36, v169, 0x3a800000, v223
	v_rsq_f32_e32 v38, v36
	v_mad_i64_i32 v[36:37], s[0:1], v168, s89, v[156:157]
	v_lshl_add_u64 v[36:37], v[36:37], 0, v[158:159]
	v_mul_f32_e32 v28, v28, v38
	v_mul_f32_e32 v29, v29, v38
	v_mul_f32_e32 v30, v30, v38
	v_mul_f32_e32 v31, v31, v38
	v_mul_f32_e32 v39, v24, v38
	v_mul_f32_e32 v48, v25, v38
	v_mul_f32_e32 v49, v26, v38
	v_mul_f32_e32 v27, v27, v38
	v_cvt_pk_bf16_f32 v24, v28, v29
	v_cvt_pk_bf16_f32 v25, v30, v31
	v_cvt_pk_bf16_f32 v26, v39, v48
	v_cvt_pk_bf16_f32 v27, v49, v27
	global_store_dwordx4 v[36:37], v[24:27], off nt
	s_nop 1
	v_mul_f32_e32 v20, v20, v38
	v_mul_f32_e32 v21, v21, v38
	v_mul_f32_e32 v22, v22, v38
	v_mul_f32_e32 v23, v23, v38
	v_mul_f32_e32 v24, v16, v38
	v_mul_f32_e32 v25, v17, v38
	v_mul_f32_e32 v26, v18, v38
	v_mul_f32_e32 v19, v19, v38
	v_cvt_pk_bf16_f32 v16, v20, v21
	v_cvt_pk_bf16_f32 v17, v22, v23
	v_cvt_pk_bf16_f32 v18, v24, v25
	v_cvt_pk_bf16_f32 v19, v26, v19
	global_store_dwordx4 v[36:37], v[16:19], off offset:256 nt
	s_nop 1
	v_fmamk_f32 v16, v167, 0x3a800000, v223
	v_rsq_f32_e32 v18, v16
	v_mad_i64_i32 v[16:17], s[0:1], v166, s89, v[156:157]
	v_lshl_add_u64 v[16:17], v[16:17], 0, v[158:159]
	v_fmac_f32_e32 v52, v12, v18
	v_mul_f32_e32 v19, v12, v18
	v_mul_f32_e32 v12, 0xbfb8aa3b, v52
	v_exp_f32_e32 v12, v12
	v_fmac_f32_e32 v53, v13, v18
	v_fmac_f32_e32 v54, v14, v18
	v_fmac_f32_e32 v55, v15, v18
	v_add_f32_e32 v12, 1.0, v12
	v_rcp_f32_e32 v12, v12
	v_fmac_f32_e32 v44, v8, v18
	v_fmac_f32_e32 v45, v9, v18
	v_fmac_f32_e32 v46, v10, v18
	v_cndmask_b32_e64 v12, v19, v12, s[42:43]
	v_mul_f32_e32 v19, v13, v18
	v_mul_f32_e32 v13, 0xbfb8aa3b, v53
	v_exp_f32_e32 v13, v13
	v_fmac_f32_e32 v47, v11, v18
	v_fmac_f32_e32 v40, v4, v18
	v_fmac_f32_e32 v41, v5, v18
	v_add_f32_e32 v13, 1.0, v13
	v_rcp_f32_e32 v13, v13
	v_fmac_f32_e32 v42, v6, v18
	v_fmac_f32_e32 v43, v7, v18
	v_fmac_f32_e32 v32, v0, v18
	v_cndmask_b32_e64 v13, v19, v13, s[42:43]
	v_mul_f32_e32 v19, v14, v18
	v_mul_f32_e32 v14, 0xbfb8aa3b, v54
	v_exp_f32_e32 v14, v14
	v_fmac_f32_e32 v33, v1, v18
	v_fmac_f32_e32 v34, v2, v18
	v_fmac_f32_e32 v35, v3, v18
	v_add_f32_e32 v14, 1.0, v14
	v_rcp_f32_e32 v14, v14
	s_mov_b64 s[0:1], -1
	v_cndmask_b32_e64 v14, v19, v14, s[42:43]
	v_mul_f32_e32 v19, v15, v18
	v_mul_f32_e32 v15, 0xbfb8aa3b, v55
	v_exp_f32_e32 v15, v15
	s_nop 0
	v_add_f32_e32 v15, 1.0, v15
	v_rcp_f32_e32 v15, v15
	s_nop 0
	v_cndmask_b32_e64 v15, v19, v15, s[42:43]
	v_mul_f32_e32 v19, v8, v18
	v_mul_f32_e32 v8, 0xbfb8aa3b, v44
	v_exp_f32_e32 v8, v8
	s_nop 0
	v_add_f32_e32 v8, 1.0, v8
	v_rcp_f32_e32 v8, v8
	s_nop 0
	v_cndmask_b32_e64 v19, v19, v8, s[42:43]
	v_mul_f32_e32 v8, v9, v18
	v_mul_f32_e32 v9, 0xbfb8aa3b, v45
	v_exp_f32_e32 v9, v9
	s_nop 0
	v_add_f32_e32 v9, 1.0, v9
	v_rcp_f32_e32 v9, v9
	s_nop 0
	v_cndmask_b32_e64 v20, v8, v9, s[42:43]
	v_mul_f32_e32 v9, 0xbfb8aa3b, v46
	v_exp_f32_e32 v9, v9
	v_mul_f32_e32 v8, v10, v18
	v_add_f32_e32 v9, 1.0, v9
	v_rcp_f32_e32 v9, v9
	s_nop 0
	v_cndmask_b32_e64 v21, v8, v9, s[42:43]
	v_mul_f32_e32 v9, 0xbfb8aa3b, v47
	v_exp_f32_e32 v9, v9
	v_mul_f32_e32 v8, v11, v18
	v_add_f32_e32 v9, 1.0, v9
	v_rcp_f32_e32 v9, v9
	s_nop 0
	v_cndmask_b32_e64 v11, v8, v9, s[42:43]
	v_cvt_pk_bf16_f32 v8, v12, v13
	v_cvt_pk_bf16_f32 v9, v14, v15
	v_cvt_pk_bf16_f32 v10, v19, v20
	v_cvt_pk_bf16_f32 v11, v21, v11
	global_store_dwordx4 v[16:17], v[8:11], off nt
	s_nop 1
	v_mul_f32_e32 v8, v4, v18
	v_mul_f32_e32 v4, 0xbfb8aa3b, v40
	v_exp_f32_e32 v4, v4
	s_nop 0
	v_add_f32_e32 v4, 1.0, v4
	v_rcp_f32_e32 v4, v4
	s_nop 0
	v_cndmask_b32_e64 v4, v8, v4, s[42:43]
	v_mul_f32_e32 v8, v5, v18
	v_mul_f32_e32 v5, 0xbfb8aa3b, v41
	v_exp_f32_e32 v5, v5
	s_nop 0
	v_add_f32_e32 v5, 1.0, v5
	v_rcp_f32_e32 v5, v5
	s_nop 0
	v_cndmask_b32_e64 v5, v8, v5, s[42:43]
	v_mul_f32_e32 v8, v6, v18
	v_mul_f32_e32 v6, 0xbfb8aa3b, v42
	v_exp_f32_e32 v6, v6
	s_nop 0
	v_add_f32_e32 v6, 1.0, v6
	v_rcp_f32_e32 v6, v6
	s_nop 0
	v_cndmask_b32_e64 v6, v8, v6, s[42:43]
	v_mul_f32_e32 v8, v7, v18
	v_mul_f32_e32 v7, 0xbfb8aa3b, v43
	v_exp_f32_e32 v7, v7
	s_nop 0
	v_add_f32_e32 v7, 1.0, v7
	v_rcp_f32_e32 v7, v7
	s_nop 0
	v_cndmask_b32_e64 v7, v8, v7, s[42:43]
	v_mul_f32_e32 v8, v0, v18
	v_mul_f32_e32 v0, 0xbfb8aa3b, v32
	v_exp_f32_e32 v0, v0
	s_nop 0
	v_add_f32_e32 v0, 1.0, v0
	v_rcp_f32_e32 v0, v0
	s_nop 0
	v_cndmask_b32_e64 v8, v8, v0, s[42:43]
	v_mul_f32_e32 v0, v1, v18
	v_mul_f32_e32 v1, 0xbfb8aa3b, v33
	v_exp_f32_e32 v1, v1
	s_nop 0
	v_add_f32_e32 v1, 1.0, v1
	v_rcp_f32_e32 v1, v1
	s_nop 0
	v_cndmask_b32_e64 v9, v0, v1, s[42:43]
	v_mul_f32_e32 v1, 0xbfb8aa3b, v34
	v_exp_f32_e32 v1, v1
	v_mul_f32_e32 v0, v2, v18
	v_add_f32_e32 v1, 1.0, v1
	v_rcp_f32_e32 v1, v1
	s_nop 0
	v_cndmask_b32_e64 v10, v0, v1, s[42:43]
	v_mul_f32_e32 v1, 0xbfb8aa3b, v35
	v_exp_f32_e32 v1, v1
	v_mul_f32_e32 v0, v3, v18
	v_add_f32_e32 v1, 1.0, v1
	v_rcp_f32_e32 v1, v1
	s_nop 0
	v_cndmask_b32_e64 v3, v0, v1, s[42:43]
	v_cvt_pk_bf16_f32 v0, v4, v5
	v_cvt_pk_bf16_f32 v1, v6, v7
	v_cvt_pk_bf16_f32 v2, v8, v9
	v_cvt_pk_bf16_f32 v3, v10, v3
	global_store_dwordx4 v[16:17], v[0:3], off offset:256 nt

; __device__ __forceinline__ unsigned cvt_pk_bf16(float lo, float hi) { unsigned r; asm volatile("v_cvt_pk_bf16_f32 %0, %1, %2" : "=v"(r) : "v"(lo), "v"(hi)); return r; }
; __device__ __forceinline__ float ror1(float x) { return __builtin_bit_cast(float, __builtin_amdgcn_update_dpp(0, __builtin_bit_cast(int, x), 0x121, 0xf, 0xf, false)); }
; __device__ __forceinline__ float ror2(float x) { return __builtin_bit_cast(float, __builtin_amdgcn_update_dpp(0, __builtin_bit_cast(int, x), 0x122, 0xf, 0xf, false)); }
;     __device__ __forceinline__ void operator()(AccT& acc, const Unit& u, int wr, int wc, int fr, int fq) const {
;     ...
;                 for (int m = 0; m < 4; ++m) {
;                     const int rl = ai * 128 + wr * 64 + m * 16 + fr;
;                     const f32x4 cg_ = acc[ai][0][m][n], cv_ = acc[ai][1][m][n];
;                     f32x4 p1g, p2g, p1v, p2v;
; #pragma unroll
;                     for (int j = 0; j < 4; ++j) {
;                         p1g[j] = ror1(fr == 15 ? hg[j] : cg_[j]); p2g[j] = ror2(fr >= 14 ? hg[j] : cg_[j]);
;                         p1v[j] = ror1(fr == 15 ? hv[j] : cv_[j]); p2v[j] = ror2(fr >= 14 ? hv[j] : cv_[j]);
;                     }
;                     const f32x4 hcg = bg + w0g * p2g + w1g * p1g + w2g * cg_;
;                     const f32x4 hcv = bv + w0v * p2v + w1v * p1v + w2v * cv_;
;                     const f32x2 ga = gelu_pk((f32x2){hcg[0], hcg[1]}), gb2 = gelu_pk((f32x2){hcg[2], hcg[3]});
;                     u32x2 w; w.x = cvt_pk_bf16(ga.x * hcv[0], ga.y * hcv[1]); w.y = cvt_pk_bf16(gb2.x * hcv[2], gb2.y * hcv[3]);
;                     const int t = tstart + rl;
;                     if (n == 0) stash[ai][m] = w;
;                     else if (rl >= 2) *(u32x4*)(U + (size_t)(arow0 + rl) * FF + colg0) = (u32x4){stash[ai][m].x, stash[ai][m].y, w.x, w.y};
;                     if (rl < 2 || rl >= 254) { float* hp = halo + ((size_t)u.pm * 4 + (rl < 2 ? rl : rl - 252)) * FF2; *(f32x4*)(hp + colg) = cg_; *(f32x4*)(hp + colv) = cv_; }
.Lmy_p5_1:
	s_or_b64 exec, exec, s[20:21]
	s_waitcnt lgkmcnt(0)
	s_nop 4
	v_mov_b32_dpp v214, v152 row_ror:1 row_mask:0xf bank_mask:0xf
	v_mov_b32_dpp v215, v153 row_ror:1 row_mask:0xf bank_mask:0xf
	v_mov_b32_dpp v216, v154 row_ror:1 row_mask:0xf bank_mask:0xf
	v_mov_b32_dpp v217, v155 row_ror:1 row_mask:0xf bank_mask:0xf
	s_nop 1
	v_cndmask_b32_e64 v164, v214, v164, s[48:49]
	v_cndmask_b32_e64 v165, v215, v165, s[48:49]
	v_cndmask_b32_e64 v166, v216, v166, s[48:49]
	v_cndmask_b32_e64 v167, v217, v167, s[48:49]
	v_mov_b32_dpp v214, v148 row_ror:1 row_mask:0xf bank_mask:0xf
	v_mov_b32_dpp v215, v149 row_ror:1 row_mask:0xf bank_mask:0xf
	v_mov_b32_dpp v216, v150 row_ror:1 row_mask:0xf bank_mask:0xf
	v_mov_b32_dpp v217, v151 row_ror:1 row_mask:0xf bank_mask:0xf
	s_nop 1
	v_cndmask_b32_e64 v168, v214, v168, s[48:49]
	v_cndmask_b32_e64 v169, v215, v169, s[48:49]
	v_cndmask_b32_e64 v170, v216, v170, s[48:49]
	v_cndmask_b32_e64 v171, v217, v171, s[48:49]
	v_mov_b32_dpp v214, v140 row_ror:1 row_mask:0xf bank_mask:0xf
	v_mov_b32_dpp v215, v141 row_ror:1 row_mask:0xf bank_mask:0xf
	v_mov_b32_dpp v216, v142 row_ror:1 row_mask:0xf bank_mask:0xf
	v_mov_b32_dpp v217, v143 row_ror:1 row_mask:0xf bank_mask:0xf
	s_nop 1
	v_cndmask_b32_e64 v234, v214, v234, s[48:49]
	v_cndmask_b32_e64 v235, v215, v235, s[48:49]
	v_cndmask_b32_e64 v236, v216, v236, s[48:49]
	v_cndmask_b32_e64 v237, v217, v237, s[48:49]
	v_mov_b32_dpp v214, v114 row_ror:1 row_mask:0xf bank_mask:0xf
	v_mov_b32_dpp v215, v115 row_ror:1 row_mask:0xf bank_mask:0xf
	v_mov_b32_dpp v216, v116 row_ror:1 row_mask:0xf bank_mask:0xf
	v_mov_b32_dpp v217, v117 row_ror:1 row_mask:0xf bank_mask:0xf
	s_nop 1
	v_cndmask_b32_e64 v250, v214, v250, s[48:49]
	v_cndmask_b32_e64 v251, v215, v251, s[48:49]
	v_cndmask_b32_e64 v252, v216, v252, s[48:49]
	v_cndmask_b32_e64 v253, v217, v253, s[48:49]
	v_pk_fma_f32 v[206:207], v[102:103], v[234:235], v[98:99]
	v_pk_fma_f32 v[210:211], v[92:93], v[250:251], v[84:85]
	v_pk_fma_f32 v[208:209], v[104:105], v[236:237], v[100:101]
	v_pk_fma_f32 v[212:213], v[94:95], v[252:253], v[86:87]
	v_pk_fma_f32 v[206:207], v[106:107], v[164:165], v[206:207]
	v_pk_fma_f32 v[210:211], v[88:89], v[168:169], v[210:211]
	v_pk_fma_f32 v[208:209], v[108:109], v[166:167], v[208:209]
	v_pk_fma_f32 v[212:213], v[90:91], v[170:171], v[212:213]
	v_pk_fma_f32 v[206:207], v[110:111], v[160:161], v[206:207]
	v_pk_fma_f32 v[210:211], v[80:81], v[156:157], v[210:211]
	v_pk_fma_f32 v[208:209], v[112:113], v[162:163], v[208:209]
	v_pk_fma_f32 v[212:213], v[82:83], v[158:159], v[212:213]
	v_fma_f32 v214, |v206|, s6, 1.0
	v_fma_f32 v215, |v207|, s6, 1.0
	v_pk_mul_f32 v[218:219], v[206:207], v[206:207]
	s_nop 0
	v_pk_mul_f32 v[218:219], v[218:219], s[36:37] op_sel_hi:[1,0]
	v_rcp_f32_e32 v214, v214
	v_rcp_f32_e32 v215, v215
	v_exp_f32_e32 v218, v218
	v_exp_f32_e32 v219, v219
	v_pk_fma_f32 v[216:217], v[214:215], s[24:25], v[186:187] op_sel_hi:[1,0,0]
	v_max_f32_e32 v220, 0, v206
	v_pk_fma_f32 v[216:217], v[214:215], v[216:217], s[28:29] op_sel_hi:[1,1,0]
	v_max_f32_e32 v221, 0, v207
	v_pk_fma_f32 v[216:217], v[214:215], v[216:217], s[30:31] op_sel_hi:[1,1,0]
	s_nop 0
	v_pk_fma_f32 v[216:217], v[214:215], v[216:217], s[34:35] op_sel_hi:[1,1,0]
	s_nop 0
	v_pk_mul_f32 v[216:217], v[214:215], v[216:217]
	s_nop 0
	v_pk_mul_f32 v[216:217], v[218:219], v[216:217]
	s_nop 0
	v_fma_f32 v206, -|v206|, v216, v220
	v_fma_f32 v207, -|v207|, v217, v221
	v_mul_f32_e32 v206, v210, v206
	v_mul_f32_e32 v207, v211, v207
	v_fma_f32 v214, |v208|, s6, 1.0
	v_fma_f32 v215, |v209|, s6, 1.0
	v_pk_mul_f32 v[218:219], v[208:209], v[208:209]
	s_nop 0
	v_pk_mul_f32 v[218:219], v[218:219], s[36:37] op_sel_hi:[1,0]
	v_rcp_f32_e32 v214, v214
	v_rcp_f32_e32 v215, v215
	v_exp_f32_e32 v218, v218
	v_exp_f32_e32 v219, v219
	v_pk_fma_f32 v[216:217], v[214:215], s[24:25], v[186:187] op_sel_hi:[1,0,0]
	v_max_f32_e32 v220, 0, v208
	v_pk_fma_f32 v[216:217], v[214:215], v[216:217], s[28:29] op_sel_hi:[1,1,0]
	v_max_f32_e32 v221, 0, v209
	v_pk_fma_f32 v[216:217], v[214:215], v[216:217], s[30:31] op_sel_hi:[1,1,0]
	s_nop 0
	v_pk_fma_f32 v[216:217], v[214:215], v[216:217], s[34:35] op_sel_hi:[1,1,0]
	s_nop 0
	v_pk_mul_f32 v[216:217], v[214:215], v[216:217]
	s_nop 0
	v_pk_mul_f32 v[216:217], v[218:219], v[216:217]
	s_nop 0
	v_fma_f32 v208, -|v208|, v216, v220
	v_fma_f32 v209, -|v209|, v217, v221
	v_mul_f32_e32 v208, v212, v208
	v_mul_f32_e32 v209, v213, v209
	v_cvt_pk_bf16_f32 v190, v206, v207
	v_cvt_pk_bf16_f32 v191, v208, v209
	s_and_saveexec_b64 s[22:23], s[74:75]
	s_cbranch_execz .Lmy_p5_2
	s_lshr_b32 s18, s16, 6
	s_add_i32 s18, s18, 0
	s_mul_i32 s18, s18, 0x5800
	s_mov_b32 s19, 0
	v_lshlrev_b64 v[214:215], 2, v[182:183]
	v_lshl_add_u64 v[214:215], s[18:19], 0, v[214:215]
	v_lshl_add_u64 v[214:215], s[92:93], 0, v[214:215]
	global_store_dwordx4 v[214:215], v[160:163], off nt
	v_lshl_add_u64 v[216:217], v[214:215], 0, s[52:53]
	global_store_dwordx4 v[216:217], v[156:159], off offset:3072 nt
; __device__ __forceinline__ unsigned cvt_pk_bf16(float lo, float hi) { unsigned r; asm volatile("v_cvt_pk_bf16_f32 %0, %1, %2" : "=v"(r) : "v"(lo), "v"(hi)); return r; }
; __device__ __forceinline__ float ror1(float x) { return __builtin_bit_cast(float, __builtin_amdgcn_update_dpp(0, __builtin_bit_cast(int, x), 0x121, 0xf, 0xf, false)); }
; __device__ __forceinline__ float ror2(float x) { return __builtin_bit_cast(float, __builtin_amdgcn_update_dpp(0, __builtin_bit_cast(int, x), 0x122, 0xf, 0xf, false)); }
;     __device__ __forceinline__ void operator()(AccT& acc, const Unit& u, int wr, int wc, int fr, int fq) const {
;     ...
;                 for (int m = 0; m < 4; ++m) {
;                     const int rl = ai * 128 + wr * 64 + m * 16 + fr;
;                     const f32x4 cg_ = acc[ai][0][m][n], cv_ = acc[ai][1][m][n];
;                     f32x4 p1g, p2g, p1v, p2v;
; #pragma unroll
;                     for (int j = 0; j < 4; ++j) {
;                         p1g[j] = ror1(fr == 15 ? hg[j] : cg_[j]); p2g[j] = ror2(fr >= 14 ? hg[j] : cg_[j]);
;                         p1v[j] = ror1(fr == 15 ? hv[j] : cv_[j]); p2v[j] = ror2(fr >= 14 ? hv[j] : cv_[j]);
;                     }
;                     const f32x4 hcg = bg + w0g * p2g + w1g * p1g + w2g * cg_;
;                     const f32x4 hcv = bv + w0v * p2v + w1v * p1v + w2v * cv_;
;                     const f32x2 ga = gelu_pk((f32x2){hcg[0], hcg[1]}), gb2 = gelu_pk((f32x2){hcg[2], hcg[3]});
;                     u32x2 w; w.x = cvt_pk_bf16(ga.x * hcv[0], ga.y * hcv[1]); w.y = cvt_pk_bf16(gb2.x * hcv[2], gb2.y * hcv[3]);
;                     const int t = tstart + rl;
;                     if (n == 0) stash[ai][m] = w;
;                     else if (rl >= 2) *(u32x4*)(U + (size_t)(arow0 + rl) * FF + colg0) = (u32x4){stash[ai][m].x, stash[ai][m].y, w.x, w.y};
;                     if (rl < 2 || rl >= 254) { float* hp = halo + ((size_t)u.pm * 4 + (rl < 2 ? rl : rl - 252)) * FF2; *(f32x4*)(hp + colg) = cg_; *(f32x4*)(hp + colv) = cv_; }
.Lmy_p5_2:
	s_or_b64 exec, exec, s[22:23]
	v_pk_fma_f32 v[206:207], v[102:103], v[164:165], v[98:99]
	v_pk_fma_f32 v[210:211], v[92:93], v[168:169], v[84:85]
	v_pk_fma_f32 v[208:209], v[104:105], v[166:167], v[100:101]
	v_pk_fma_f32 v[212:213], v[94:95], v[170:171], v[86:87]
	v_pk_fma_f32 v[206:207], v[106:107], v[160:161], v[206:207]
	v_pk_fma_f32 v[210:211], v[88:89], v[156:157], v[210:211]
	v_pk_fma_f32 v[208:209], v[108:109], v[162:163], v[208:209]
	v_pk_fma_f32 v[212:213], v[90:91], v[158:159], v[212:213]
	v_pk_fma_f32 v[206:207], v[110:111], v[144:145], v[206:207]
	v_pk_fma_f32 v[210:211], v[80:81], v[118:119], v[210:211]
	v_pk_fma_f32 v[208:209], v[112:113], v[146:147], v[208:209]
	v_pk_fma_f32 v[212:213], v[82:83], v[120:121], v[212:213]
	v_fma_f32 v214, |v206|, s6, 1.0
	v_fma_f32 v215, |v207|, s6, 1.0
	v_pk_mul_f32 v[218:219], v[206:207], v[206:207]
	s_nop 0
	v_pk_mul_f32 v[218:219], v[218:219], s[36:37] op_sel_hi:[1,0]
	v_rcp_f32_e32 v214, v214
	v_rcp_f32_e32 v215, v215
	v_exp_f32_e32 v218, v218
	v_exp_f32_e32 v219, v219
	v_pk_fma_f32 v[216:217], v[214:215], s[24:25], v[186:187] op_sel_hi:[1,0,0]
	v_max_f32_e32 v220, 0, v206
	v_pk_fma_f32 v[216:217], v[214:215], v[216:217], s[28:29] op_sel_hi:[1,1,0]
	v_max_f32_e32 v221, 0, v207
	v_pk_fma_f32 v[216:217], v[214:215], v[216:217], s[30:31] op_sel_hi:[1,1,0]
	s_nop 0
	v_pk_fma_f32 v[216:217], v[214:215], v[216:217], s[34:35] op_sel_hi:[1,1,0]
	s_nop 0
	v_pk_mul_f32 v[216:217], v[214:215], v[216:217]
	s_nop 0
	v_pk_mul_f32 v[216:217], v[218:219], v[216:217]
	s_nop 0
	v_fma_f32 v206, -|v206|, v216, v220
	v_fma_f32 v207, -|v207|, v217, v221
	v_mul_f32_e32 v206, v210, v206
	v_mul_f32_e32 v207, v211, v207
	v_fma_f32 v214, |v208|, s6, 1.0
	v_fma_f32 v215, |v209|, s6, 1.0
	v_pk_mul_f32 v[218:219], v[208:209], v[208:209]
	s_nop 0
	v_pk_mul_f32 v[218:219], v[218:219], s[36:37] op_sel_hi:[1,0]
	v_rcp_f32_e32 v214, v214
	v_rcp_f32_e32 v215, v215
	v_exp_f32_e32 v218, v218
	v_exp_f32_e32 v219, v219
	v_pk_fma_f32 v[216:217], v[214:215], s[24:25], v[186:187] op_sel_hi:[1,0,0]
	v_max_f32_e32 v220, 0, v208
	v_pk_fma_f32 v[216:217], v[214:215], v[216:217], s[28:29] op_sel_hi:[1,1,0]
	v_max_f32_e32 v221, 0, v209
	v_pk_fma_f32 v[216:217], v[214:215], v[216:217], s[30:31] op_sel_hi:[1,1,0]
	s_nop 0
	v_pk_fma_f32 v[216:217], v[214:215], v[216:217], s[34:35] op_sel_hi:[1,1,0]
	s_nop 0
	v_pk_mul_f32 v[216:217], v[214:215], v[216:217]
	s_nop 0
	v_pk_mul_f32 v[216:217], v[218:219], v[216:217]
	s_nop 0
	v_fma_f32 v208, -|v208|, v216, v220
	v_fma_f32 v209, -|v209|, v217, v221
	v_mul_f32_e32 v208, v212, v208
	v_mul_f32_e32 v209, v213, v209
	v_cvt_pk_bf16_f32 v238, v206, v207
	v_cvt_pk_bf16_f32 v239, v208, v209
	s_and_saveexec_b64 s[22:23], s[74:75]
	s_cbranch_execz .Lmy_p5_3
	s_lshr_b32 s18, s16, 6
	s_add_i32 s18, s18, 1
	s_mul_i32 s18, s18, 0x5800
	s_mov_b32 s19, 0
	v_lshlrev_b64 v[214:215], 2, v[182:183]
	v_lshl_add_u64 v[214:215], s[18:19], 0, v[214:215]
	v_lshl_add_u64 v[214:215], s[92:93], 0, v[214:215]
	global_store_dwordx4 v[214:215], v[144:147], off nt
	v_lshl_add_u64 v[216:217], v[214:215], 0, s[52:53]
	global_store_dwordx4 v[216:217], v[118:121], off offset:3072 nt

; __device__ __forceinline__ unsigned cvt_pk_bf16(float lo, float hi) { unsigned r; asm volatile("v_cvt_pk_bf16_f32 %0, %1, %2" : "=v"(r) : "v"(lo), "v"(hi)); return r; }
; __device__ __forceinline__ float ror1(float x) { return __builtin_bit_cast(float, __builtin_amdgcn_update_dpp(0, __builtin_bit_cast(int, x), 0x121, 0xf, 0xf, false)); }
; __device__ __forceinline__ float ror2(float x) { return __builtin_bit_cast(float, __builtin_amdgcn_update_dpp(0, __builtin_bit_cast(int, x), 0x122, 0xf, 0xf, false)); }
;     __device__ __forceinline__ void operator()(AccT& acc, const Unit& u, int wr, int wc, int fr, int fq) const {
;     ...
;                 for (int m = 0; m < 4; ++m) {
;                     const int rl = ai * 128 + wr * 64 + m * 16 + fr;
;                     const f32x4 cg_ = acc[ai][0][m][n], cv_ = acc[ai][1][m][n];
;                     f32x4 p1g, p2g, p1v, p2v;
; #pragma unroll
;                     for (int j = 0; j < 4; ++j) {
;                         p1g[j] = ror1(fr == 15 ? hg[j] : cg_[j]); p2g[j] = ror2(fr >= 14 ? hg[j] : cg_[j]);
;                         p1v[j] = ror1(fr == 15 ? hv[j] : cv_[j]); p2v[j] = ror2(fr >= 14 ? hv[j] : cv_[j]);
;                     }
;                     const f32x4 hcg = bg + w0g * p2g + w1g * p1g + w2g * cg_;
;                     const f32x4 hcv = bv + w0v * p2v + w1v * p1v + w2v * cv_;
;                     const f32x2 ga = gelu_pk((f32x2){hcg[0], hcg[1]}), gb2 = gelu_pk((f32x2){hcg[2], hcg[3]});
;                     u32x2 w; w.x = cvt_pk_bf16(ga.x * hcv[0], ga.y * hcv[1]); w.y = cvt_pk_bf16(gb2.x * hcv[2], gb2.y * hcv[3]);
;                     const int t = tstart + rl;
;                     if (n == 0) stash[ai][m] = w;
;                     else if (rl >= 2) *(u32x4*)(U + (size_t)(arow0 + rl) * FF + colg0) = (u32x4){stash[ai][m].x, stash[ai][m].y, w.x, w.y};
;                     if (rl < 2 || rl >= 254) { float* hp = halo + ((size_t)u.pm * 4 + (rl < 2 ? rl : rl - 252)) * FF2; *(f32x4*)(hp + colg) = cg_; *(f32x4*)(hp + colv) = cv_; }
.Lmy_p5_4:
	s_or_b64 exec, exec, s[20:21]
	s_waitcnt lgkmcnt(0)
	s_nop 4
	v_mov_b32_dpp v214, v122 row_ror:1 row_mask:0xf bank_mask:0xf
	v_mov_b32_dpp v215, v123 row_ror:1 row_mask:0xf bank_mask:0xf
	v_mov_b32_dpp v216, v124 row_ror:1 row_mask:0xf bank_mask:0xf
	v_mov_b32_dpp v217, v125 row_ror:1 row_mask:0xf bank_mask:0xf
	s_nop 1
	v_cndmask_b32_e64 v164, v214, v164, s[48:49]
	v_cndmask_b32_e64 v165, v215, v165, s[48:49]
	v_cndmask_b32_e64 v166, v216, v166, s[48:49]
	v_cndmask_b32_e64 v167, v217, v167, s[48:49]
	v_mov_b32_dpp v214, v128 row_ror:1 row_mask:0xf bank_mask:0xf
	v_mov_b32_dpp v215, v129 row_ror:1 row_mask:0xf bank_mask:0xf
	v_mov_b32_dpp v216, v130 row_ror:1 row_mask:0xf bank_mask:0xf
	v_mov_b32_dpp v217, v131 row_ror:1 row_mask:0xf bank_mask:0xf
	s_nop 1
	v_cndmask_b32_e64 v168, v214, v168, s[48:49]
	v_cndmask_b32_e64 v169, v215, v169, s[48:49]
	v_cndmask_b32_e64 v170, v216, v170, s[48:49]
	v_cndmask_b32_e64 v171, v217, v171, s[48:49]
	v_mov_b32_dpp v214, v68 row_ror:1 row_mask:0xf bank_mask:0xf
	v_mov_b32_dpp v215, v69 row_ror:1 row_mask:0xf bank_mask:0xf
	v_mov_b32_dpp v216, v70 row_ror:1 row_mask:0xf bank_mask:0xf
	v_mov_b32_dpp v217, v71 row_ror:1 row_mask:0xf bank_mask:0xf
	s_nop 1
	v_cndmask_b32_e64 v234, v214, v234, s[48:49]
	v_cndmask_b32_e64 v235, v215, v235, s[48:49]
	v_cndmask_b32_e64 v236, v216, v236, s[48:49]
	v_cndmask_b32_e64 v237, v217, v237, s[48:49]
	v_mov_b32_dpp v214, v64 row_ror:1 row_mask:0xf bank_mask:0xf
	v_mov_b32_dpp v215, v65 row_ror:1 row_mask:0xf bank_mask:0xf
	v_mov_b32_dpp v216, v66 row_ror:1 row_mask:0xf bank_mask:0xf
	v_mov_b32_dpp v217, v67 row_ror:1 row_mask:0xf bank_mask:0xf
	s_nop 1
	v_cndmask_b32_e64 v250, v214, v250, s[48:49]
	v_cndmask_b32_e64 v251, v215, v251, s[48:49]
	v_cndmask_b32_e64 v252, v216, v252, s[48:49]
	v_cndmask_b32_e64 v253, v217, v253, s[48:49]
	v_pk_fma_f32 v[206:207], v[102:103], v[234:235], v[98:99]
	v_pk_fma_f32 v[210:211], v[92:93], v[250:251], v[84:85]
	v_pk_fma_f32 v[208:209], v[104:105], v[236:237], v[100:101]
	v_pk_fma_f32 v[212:213], v[94:95], v[252:253], v[86:87]
	v_pk_fma_f32 v[206:207], v[106:107], v[164:165], v[206:207]
	v_pk_fma_f32 v[210:211], v[88:89], v[168:169], v[210:211]
	v_pk_fma_f32 v[208:209], v[108:109], v[166:167], v[208:209]
	v_pk_fma_f32 v[212:213], v[90:91], v[170:171], v[212:213]
	v_pk_fma_f32 v[206:207], v[110:111], v[136:137], v[206:207]
	v_pk_fma_f32 v[210:211], v[80:81], v[132:133], v[210:211]
	v_pk_fma_f32 v[208:209], v[112:113], v[138:139], v[208:209]
	v_pk_fma_f32 v[212:213], v[82:83], v[134:135], v[212:213]
	v_fma_f32 v214, |v206|, s6, 1.0
	v_fma_f32 v215, |v207|, s6, 1.0
	v_pk_mul_f32 v[218:219], v[206:207], v[206:207]
	s_nop 0
	v_pk_mul_f32 v[218:219], v[218:219], s[36:37] op_sel_hi:[1,0]
	v_rcp_f32_e32 v214, v214
	v_rcp_f32_e32 v215, v215
	v_exp_f32_e32 v218, v218
	v_exp_f32_e32 v219, v219
	v_pk_fma_f32 v[216:217], v[214:215], s[24:25], v[186:187] op_sel_hi:[1,0,0]
	v_max_f32_e32 v220, 0, v206
	v_pk_fma_f32 v[216:217], v[214:215], v[216:217], s[28:29] op_sel_hi:[1,1,0]
	v_max_f32_e32 v221, 0, v207
	v_pk_fma_f32 v[216:217], v[214:215], v[216:217], s[30:31] op_sel_hi:[1,1,0]
	s_nop 0
	v_pk_fma_f32 v[216:217], v[214:215], v[216:217], s[34:35] op_sel_hi:[1,1,0]
	s_nop 0
	v_pk_mul_f32 v[216:217], v[214:215], v[216:217]
	s_nop 0
	v_pk_mul_f32 v[216:217], v[218:219], v[216:217]
	s_nop 0
	v_fma_f32 v206, -|v206|, v216, v220
	v_fma_f32 v207, -|v207|, v217, v221
	v_mul_f32_e32 v206, v210, v206
	v_mul_f32_e32 v207, v211, v207
	v_fma_f32 v214, |v208|, s6, 1.0
	v_fma_f32 v215, |v209|, s6, 1.0
	v_pk_mul_f32 v[218:219], v[208:209], v[208:209]
	s_nop 0
	v_pk_mul_f32 v[218:219], v[218:219], s[36:37] op_sel_hi:[1,0]
	v_rcp_f32_e32 v214, v214
	v_rcp_f32_e32 v215, v215
	v_exp_f32_e32 v218, v218
	v_exp_f32_e32 v219, v219
	v_pk_fma_f32 v[216:217], v[214:215], s[24:25], v[186:187] op_sel_hi:[1,0,0]
	v_max_f32_e32 v220, 0, v208
	v_pk_fma_f32 v[216:217], v[214:215], v[216:217], s[28:29] op_sel_hi:[1,1,0]
	v_max_f32_e32 v221, 0, v209
	v_pk_fma_f32 v[216:217], v[214:215], v[216:217], s[30:31] op_sel_hi:[1,1,0]
	s_nop 0
	v_pk_fma_f32 v[216:217], v[214:215], v[216:217], s[34:35] op_sel_hi:[1,1,0]
	s_nop 0
	v_pk_mul_f32 v[216:217], v[214:215], v[216:217]
	s_nop 0
	v_pk_mul_f32 v[216:217], v[218:219], v[216:217]
	s_nop 0
	v_fma_f32 v208, -|v208|, v216, v220
	v_fma_f32 v209, -|v209|, v217, v221
	v_mul_f32_e32 v208, v212, v208
	v_mul_f32_e32 v209, v213, v209
	v_cvt_pk_bf16_f32 v156, v206, v207
	v_cvt_pk_bf16_f32 v157, v208, v209
	v_pk_fma_f32 v[206:207], v[102:103], v[164:165], v[98:99]
	v_pk_fma_f32 v[210:211], v[92:93], v[168:169], v[84:85]
	v_pk_fma_f32 v[208:209], v[104:105], v[166:167], v[100:101]
	v_pk_fma_f32 v[212:213], v[94:95], v[170:171], v[86:87]
	v_pk_fma_f32 v[206:207], v[106:107], v[136:137], v[206:207]
	v_pk_fma_f32 v[210:211], v[88:89], v[132:133], v[210:211]
	v_pk_fma_f32 v[208:209], v[108:109], v[138:139], v[208:209]
	v_pk_fma_f32 v[212:213], v[90:91], v[134:135], v[212:213]
	v_pk_fma_f32 v[206:207], v[110:111], v[76:77], v[206:207]
	v_pk_fma_f32 v[210:211], v[80:81], v[72:73], v[210:211]
	v_pk_fma_f32 v[208:209], v[112:113], v[78:79], v[208:209]
	v_pk_fma_f32 v[212:213], v[82:83], v[74:75], v[212:213]
	v_fma_f32 v214, |v206|, s6, 1.0
	v_fma_f32 v215, |v207|, s6, 1.0
	v_pk_mul_f32 v[218:219], v[206:207], v[206:207]
	s_nop 0
	v_pk_mul_f32 v[218:219], v[218:219], s[36:37] op_sel_hi:[1,0]
	v_rcp_f32_e32 v214, v214
	v_rcp_f32_e32 v215, v215
	v_exp_f32_e32 v218, v218
	v_exp_f32_e32 v219, v219
	v_pk_fma_f32 v[216:217], v[214:215], s[24:25], v[186:187] op_sel_hi:[1,0,0]
	v_max_f32_e32 v220, 0, v206
	v_pk_fma_f32 v[216:217], v[214:215], v[216:217], s[28:29] op_sel_hi:[1,1,0]
; __device__ __forceinline__ unsigned cvt_pk_bf16(float lo, float hi) { unsigned r; asm volatile("v_cvt_pk_bf16_f32 %0, %1, %2" : "=v"(r) : "v"(lo), "v"(hi)); return r; }
; __device__ __forceinline__ float ror1(float x) { return __builtin_bit_cast(float, __builtin_amdgcn_update_dpp(0, __builtin_bit_cast(int, x), 0x121, 0xf, 0xf, false)); }
; __device__ __forceinline__ float ror2(float x) { return __builtin_bit_cast(float, __builtin_amdgcn_update_dpp(0, __builtin_bit_cast(int, x), 0x122, 0xf, 0xf, false)); }
;     __device__ __forceinline__ void operator()(AccT& acc, const Unit& u, int wr, int wc, int fr, int fq) const {
;     ...
;                 for (int m = 0; m < 4; ++m) {
;                     const int rl = ai * 128 + wr * 64 + m * 16 + fr;
;                     const f32x4 cg_ = acc[ai][0][m][n], cv_ = acc[ai][1][m][n];
;                     f32x4 p1g, p2g, p1v, p2v;
; #pragma unroll
;                     for (int j = 0; j < 4; ++j) {
;                         p1g[j] = ror1(fr == 15 ? hg[j] : cg_[j]); p2g[j] = ror2(fr >= 14 ? hg[j] : cg_[j]);
;                         p1v[j] = ror1(fr == 15 ? hv[j] : cv_[j]); p2v[j] = ror2(fr >= 14 ? hv[j] : cv_[j]);
;                     }
;                     const f32x4 hcg = bg + w0g * p2g + w1g * p1g + w2g * cg_;
;                     const f32x4 hcv = bv + w0v * p2v + w1v * p1v + w2v * cv_;
;                     const f32x2 ga = gelu_pk((f32x2){hcg[0], hcg[1]}), gb2 = gelu_pk((f32x2){hcg[2], hcg[3]});
;                     u32x2 w; w.x = cvt_pk_bf16(ga.x * hcv[0], ga.y * hcv[1]); w.y = cvt_pk_bf16(gb2.x * hcv[2], gb2.y * hcv[3]);
;                     const int t = tstart + rl;
;                     if (n == 0) stash[ai][m] = w;
;                     else if (rl >= 2) *(u32x4*)(U + (size_t)(arow0 + rl) * FF + colg0) = (u32x4){stash[ai][m].x, stash[ai][m].y, w.x, w.y};
;                     if (rl < 2 || rl >= 254) { float* hp = halo + ((size_t)u.pm * 4 + (rl < 2 ? rl : rl - 252)) * FF2; *(f32x4*)(hp + colg) = cg_; *(f32x4*)(hp + colv) = cv_; }
;                     if (t >= SEQ - 2) { float* cp = conv_p + (size_t)(b * 2 + (t - (SEQ - 2))) * FF2; *(f32x4*)(cp + colg) = cg_; *(f32x4*)(cp + colv) = cv_; }
	v_max_f32_e32 v221, 0, v207
	v_pk_fma_f32 v[216:217], v[214:215], v[216:217], s[30:31] op_sel_hi:[1,1,0]
	s_nop 0
	v_pk_fma_f32 v[216:217], v[214:215], v[216:217], s[34:35] op_sel_hi:[1,1,0]
	s_nop 0
	v_pk_mul_f32 v[216:217], v[214:215], v[216:217]
	s_nop 0
	v_pk_mul_f32 v[216:217], v[218:219], v[216:217]
	s_nop 0
	v_fma_f32 v206, -|v206|, v216, v220
	v_fma_f32 v207, -|v207|, v217, v221
	v_mul_f32_e32 v206, v210, v206
	v_mul_f32_e32 v207, v211, v207
	v_fma_f32 v214, |v208|, s6, 1.0
	v_fma_f32 v215, |v209|, s6, 1.0
	v_pk_mul_f32 v[218:219], v[208:209], v[208:209]
	s_nop 0
	v_pk_mul_f32 v[218:219], v[218:219], s[36:37] op_sel_hi:[1,0]
	v_rcp_f32_e32 v214, v214
	v_rcp_f32_e32 v215, v215
	v_exp_f32_e32 v218, v218
	v_exp_f32_e32 v219, v219
	v_pk_fma_f32 v[216:217], v[214:215], s[24:25], v[186:187] op_sel_hi:[1,0,0]
	v_max_f32_e32 v220, 0, v208
	v_pk_fma_f32 v[216:217], v[214:215], v[216:217], s[28:29] op_sel_hi:[1,1,0]
	v_max_f32_e32 v221, 0, v209
	v_pk_fma_f32 v[216:217], v[214:215], v[216:217], s[30:31] op_sel_hi:[1,1,0]
	s_nop 0
	v_pk_fma_f32 v[216:217], v[214:215], v[216:217], s[34:35] op_sel_hi:[1,1,0]
	s_nop 0
	v_pk_mul_f32 v[216:217], v[214:215], v[216:217]
	s_nop 0
	v_pk_mul_f32 v[216:217], v[218:219], v[216:217]
	s_nop 0
	v_fma_f32 v208, -|v208|, v216, v220
	v_fma_f32 v209, -|v209|, v217, v221
	v_mul_f32_e32 v208, v212, v208
	v_mul_f32_e32 v209, v213, v209
	v_cvt_pk_bf16_f32 v118, v206, v207
	v_cvt_pk_bf16_f32 v119, v208, v209
	v_pk_fma_f32 v[206:207], v[102:103], v[136:137], v[98:99]
	v_pk_fma_f32 v[210:211], v[92:93], v[132:133], v[84:85]
	v_pk_fma_f32 v[208:209], v[104:105], v[138:139], v[100:101]
	v_pk_fma_f32 v[212:213], v[94:95], v[134:135], v[86:87]
	v_pk_fma_f32 v[206:207], v[106:107], v[76:77], v[206:207]
	v_pk_fma_f32 v[210:211], v[88:89], v[72:73], v[210:211]
	v_pk_fma_f32 v[208:209], v[108:109], v[78:79], v[208:209]
	v_pk_fma_f32 v[212:213], v[90:91], v[74:75], v[212:213]
	v_pk_fma_f32 v[206:207], v[110:111], v[68:69], v[206:207]
	v_pk_fma_f32 v[210:211], v[80:81], v[64:65], v[210:211]
	v_pk_fma_f32 v[208:209], v[112:113], v[70:71], v[208:209]
	v_pk_fma_f32 v[212:213], v[82:83], v[66:67], v[212:213]
	v_fma_f32 v214, |v206|, s6, 1.0
	v_fma_f32 v215, |v207|, s6, 1.0
	v_pk_mul_f32 v[218:219], v[206:207], v[206:207]
	s_nop 0
	v_pk_mul_f32 v[218:219], v[218:219], s[36:37] op_sel_hi:[1,0]
	v_rcp_f32_e32 v214, v214
	v_rcp_f32_e32 v215, v215
	v_exp_f32_e32 v218, v218
	v_exp_f32_e32 v219, v219
	v_pk_fma_f32 v[216:217], v[214:215], s[24:25], v[186:187] op_sel_hi:[1,0,0]
	v_max_f32_e32 v220, 0, v206
	v_pk_fma_f32 v[216:217], v[214:215], v[216:217], s[28:29] op_sel_hi:[1,1,0]
	v_max_f32_e32 v221, 0, v207
	v_pk_fma_f32 v[216:217], v[214:215], v[216:217], s[30:31] op_sel_hi:[1,1,0]
	s_nop 0
	v_pk_fma_f32 v[216:217], v[214:215], v[216:217], s[34:35] op_sel_hi:[1,1,0]
	s_nop 0
	v_pk_mul_f32 v[216:217], v[214:215], v[216:217]
	s_nop 0
	v_pk_mul_f32 v[216:217], v[218:219], v[216:217]
	s_nop 0
	v_fma_f32 v206, -|v206|, v216, v220
	v_fma_f32 v207, -|v207|, v217, v221
	v_mul_f32_e32 v206, v210, v206
	v_mul_f32_e32 v207, v211, v207
	v_fma_f32 v214, |v208|, s6, 1.0
	v_fma_f32 v215, |v209|, s6, 1.0
	v_pk_mul_f32 v[218:219], v[208:209], v[208:209]
	s_nop 0
	v_pk_mul_f32 v[218:219], v[218:219], s[36:37] op_sel_hi:[1,0]
	v_rcp_f32_e32 v214, v214
	v_rcp_f32_e32 v215, v215
	v_exp_f32_e32 v218, v218
	v_exp_f32_e32 v219, v219
	v_pk_fma_f32 v[216:217], v[214:215], s[24:25], v[186:187] op_sel_hi:[1,0,0]
	v_max_f32_e32 v220, 0, v208
	v_pk_fma_f32 v[216:217], v[214:215], v[216:217], s[28:29] op_sel_hi:[1,1,0]
	v_max_f32_e32 v221, 0, v209
	v_pk_fma_f32 v[216:217], v[214:215], v[216:217], s[30:31] op_sel_hi:[1,1,0]
	s_nop 0
	v_pk_fma_f32 v[216:217], v[214:215], v[216:217], s[34:35] op_sel_hi:[1,1,0]
	s_nop 0
	v_pk_mul_f32 v[216:217], v[214:215], v[216:217]
	s_nop 0
	v_pk_mul_f32 v[216:217], v[218:219], v[216:217]
	s_nop 0
	v_fma_f32 v208, -|v208|, v216, v220
	v_fma_f32 v209, -|v209|, v217, v221
	v_mul_f32_e32 v208, v212, v208
	v_mul_f32_e32 v209, v213, v209
	v_cvt_pk_bf16_f32 v140, v206, v207
	v_cvt_pk_bf16_f32 v141, v208, v209
	s_and_saveexec_b64 s[22:23], s[76:77]
	s_cbranch_execz .Lmy_p5_5
	s_lshr_b32 s18, s16, 6
	s_add_i32 s18, s18, 2
	s_mul_i32 s18, s18, 0x5800
	s_mov_b32 s19, 0
	v_lshlrev_b64 v[214:215], 2, v[182:183]
	v_lshl_add_u64 v[214:215], s[18:19], 0, v[214:215]
	v_lshl_add_u64 v[214:215], s[92:93], 0, v[214:215]
	global_store_dwordx4 v[214:215], v[68:71], off nt
	v_lshl_add_u64 v[216:217], v[214:215], 0, s[52:53]
	global_store_dwordx4 v[216:217], v[64:67], off offset:3072 nt
	s_bfe_u32 s18, s16, 0x60008
	s_cmp_eq_u32 s18, 63
	s_cbranch_scc0 .Lmy_p5_5
	s_lshr_b32 s18, s16, 14
	s_lshl_b32 s18, s18, 1
	s_add_i32 s18, s18, 0
	s_mul_i32 s18, s18, 0x5800
	s_mov_b32 s19, 0
	v_lshlrev_b64 v[214:215], 2, v[182:183]
	v_lshl_add_u64 v[214:215], s[18:19], 0, v[214:215]
	v_lshl_add_u64 v[214:215], s[0:1], 0, v[214:215]
	global_store_dwordx4 v[214:215], v[68:71], off nt
	v_lshl_add_u64 v[216:217], v[214:215], 0, s[52:53]
	global_store_dwordx4 v[216:217], v[64:67], off offset:3072 nt
; __device__ __forceinline__ unsigned cvt_pk_bf16(float lo, float hi) { unsigned r; asm volatile("v_cvt_pk_bf16_f32 %0, %1, %2" : "=v"(r) : "v"(lo), "v"(hi)); return r; }
; __device__ __forceinline__ float ror1(float x) { return __builtin_bit_cast(float, __builtin_amdgcn_update_dpp(0, __builtin_bit_cast(int, x), 0x121, 0xf, 0xf, false)); }
; __device__ __forceinline__ float ror2(float x) { return __builtin_bit_cast(float, __builtin_amdgcn_update_dpp(0, __builtin_bit_cast(int, x), 0x122, 0xf, 0xf, false)); }
;     __device__ __forceinline__ void operator()(AccT& acc, const Unit& u, int wr, int wc, int fr, int fq) const {
;     ...
;                 for (int m = 0; m < 4; ++m) {
;                     const int rl = ai * 128 + wr * 64 + m * 16 + fr;
;                     const f32x4 cg_ = acc[ai][0][m][n], cv_ = acc[ai][1][m][n];
;                     f32x4 p1g, p2g, p1v, p2v;
; #pragma unroll
;                     for (int j = 0; j < 4; ++j) {
;                         p1g[j] = ror1(fr == 15 ? hg[j] : cg_[j]); p2g[j] = ror2(fr >= 14 ? hg[j] : cg_[j]);
;                         p1v[j] = ror1(fr == 15 ? hv[j] : cv_[j]); p2v[j] = ror2(fr >= 14 ? hv[j] : cv_[j]);
;                     }
;                     const f32x4 hcg = bg + w0g * p2g + w1g * p1g + w2g * cg_;
;                     const f32x4 hcv = bv + w0v * p2v + w1v * p1v + w2v * cv_;
;                     const f32x2 ga = gelu_pk((f32x2){hcg[0], hcg[1]}), gb2 = gelu_pk((f32x2){hcg[2], hcg[3]});
;                     u32x2 w; w.x = cvt_pk_bf16(ga.x * hcv[0], ga.y * hcv[1]); w.y = cvt_pk_bf16(gb2.x * hcv[2], gb2.y * hcv[3]);
;                     const int t = tstart + rl;
;                     if (n == 0) stash[ai][m] = w;
;                     else if (rl >= 2) *(u32x4*)(U + (size_t)(arow0 + rl) * FF + colg0) = (u32x4){stash[ai][m].x, stash[ai][m].y, w.x, w.y};
;                     if (rl < 2 || rl >= 254) { float* hp = halo + ((size_t)u.pm * 4 + (rl < 2 ? rl : rl - 252)) * FF2; *(f32x4*)(hp + colg) = cg_; *(f32x4*)(hp + colv) = cv_; }
;                     if (t >= SEQ - 2) { float* cp = conv_p + (size_t)(b * 2 + (t - (SEQ - 2))) * FF2; *(f32x4*)(cp + colg) = cg_; *(f32x4*)(cp + colv) = cv_; }
.Lmy_p5_5:
	s_or_b64 exec, exec, s[22:23]
	v_pk_fma_f32 v[206:207], v[102:103], v[76:77], v[98:99]
	v_pk_fma_f32 v[210:211], v[92:93], v[72:73], v[84:85]
	v_pk_fma_f32 v[208:209], v[104:105], v[78:79], v[100:101]
	v_pk_fma_f32 v[212:213], v[94:95], v[74:75], v[86:87]
	v_pk_fma_f32 v[206:207], v[106:107], v[68:69], v[206:207]
	v_pk_fma_f32 v[210:211], v[88:89], v[64:65], v[210:211]
	v_pk_fma_f32 v[208:209], v[108:109], v[70:71], v[208:209]
	v_pk_fma_f32 v[212:213], v[90:91], v[66:67], v[212:213]
	v_pk_fma_f32 v[206:207], v[110:111], v[122:123], v[206:207]
	v_pk_fma_f32 v[210:211], v[80:81], v[128:129], v[210:211]
	v_pk_fma_f32 v[208:209], v[112:113], v[124:125], v[208:209]
	v_pk_fma_f32 v[212:213], v[82:83], v[130:131], v[212:213]
	v_fma_f32 v214, |v206|, s6, 1.0
	v_fma_f32 v215, |v207|, s6, 1.0
	v_pk_mul_f32 v[218:219], v[206:207], v[206:207]
	s_nop 0
	v_pk_mul_f32 v[218:219], v[218:219], s[36:37] op_sel_hi:[1,0]
	v_rcp_f32_e32 v214, v214
	v_rcp_f32_e32 v215, v215
	v_exp_f32_e32 v218, v218
	v_exp_f32_e32 v219, v219
	v_pk_fma_f32 v[216:217], v[214:215], s[24:25], v[186:187] op_sel_hi:[1,0,0]
	v_max_f32_e32 v220, 0, v206
	v_pk_fma_f32 v[216:217], v[214:215], v[216:217], s[28:29] op_sel_hi:[1,1,0]
	v_max_f32_e32 v221, 0, v207
	v_pk_fma_f32 v[216:217], v[214:215], v[216:217], s[30:31] op_sel_hi:[1,1,0]
	s_nop 0
	v_pk_fma_f32 v[216:217], v[214:215], v[216:217], s[34:35] op_sel_hi:[1,1,0]
	s_nop 0
	v_pk_mul_f32 v[216:217], v[214:215], v[216:217]
	s_nop 0
	v_pk_mul_f32 v[216:217], v[218:219], v[216:217]
	s_nop 0
	v_fma_f32 v206, -|v206|, v216, v220
	v_fma_f32 v207, -|v207|, v217, v221
	v_mul_f32_e32 v206, v210, v206
	v_mul_f32_e32 v207, v211, v207
	v_fma_f32 v214, |v208|, s6, 1.0
	v_fma_f32 v215, |v209|, s6, 1.0
	v_pk_mul_f32 v[218:219], v[208:209], v[208:209]
	s_nop 0
	v_pk_mul_f32 v[218:219], v[218:219], s[36:37] op_sel_hi:[1,0]
	v_rcp_f32_e32 v214, v214
	v_rcp_f32_e32 v215, v215
	v_exp_f32_e32 v218, v218
	v_exp_f32_e32 v219, v219
	v_pk_fma_f32 v[216:217], v[214:215], s[24:25], v[186:187] op_sel_hi:[1,0,0]
	v_max_f32_e32 v220, 0, v208
	v_pk_fma_f32 v[216:217], v[214:215], v[216:217], s[28:29] op_sel_hi:[1,1,0]
	v_max_f32_e32 v221, 0, v209
	v_pk_fma_f32 v[216:217], v[214:215], v[216:217], s[30:31] op_sel_hi:[1,1,0]
	s_nop 0
	v_pk_fma_f32 v[216:217], v[214:215], v[216:217], s[34:35] op_sel_hi:[1,1,0]
	s_nop 0
	v_pk_mul_f32 v[216:217], v[214:215], v[216:217]
	s_nop 0
	v_pk_mul_f32 v[216:217], v[218:219], v[216:217]
	s_nop 0
	v_fma_f32 v208, -|v208|, v216, v220
	v_fma_f32 v209, -|v209|, v217, v221
	v_mul_f32_e32 v208, v212, v208
	v_mul_f32_e32 v209, v213, v209
	v_cvt_pk_bf16_f32 v152, v206, v207
	v_cvt_pk_bf16_f32 v153, v208, v209
	s_and_saveexec_b64 s[22:23], s[76:77]
	s_cbranch_execz .Lmy_p5_6
	s_lshr_b32 s18, s16, 6
	s_add_i32 s18, s18, 3
	s_mul_i32 s18, s18, 0x5800
	s_mov_b32 s19, 0
	v_lshlrev_b64 v[214:215], 2, v[182:183]
	v_lshl_add_u64 v[214:215], s[18:19], 0, v[214:215]
	v_lshl_add_u64 v[214:215], s[92:93], 0, v[214:215]
	global_store_dwordx4 v[214:215], v[122:125], off nt
	v_lshl_add_u64 v[216:217], v[214:215], 0, s[52:53]
	global_store_dwordx4 v[216:217], v[128:131], off offset:3072 nt
	s_bfe_u32 s18, s16, 0x60008
	s_cmp_eq_u32 s18, 63
	s_cbranch_scc0 .Lmy_p5_6
	s_lshr_b32 s18, s16, 14
	s_lshl_b32 s18, s18, 1
	s_add_i32 s18, s18, 1
	s_mul_i32 s18, s18, 0x5800
	s_mov_b32 s19, 0
	v_lshlrev_b64 v[214:215], 2, v[182:183]
	v_lshl_add_u64 v[214:215], s[18:19], 0, v[214:215]
	v_lshl_add_u64 v[214:215], s[0:1], 0, v[214:215]
	global_store_dwordx4 v[214:215], v[122:125], off nt
	v_lshl_add_u64 v[216:217], v[214:215], 0, s[52:53]
	global_store_dwordx4 v[216:217], v[128:131], off offset:3072 nt

; __device__ __forceinline__ unsigned cvt_pk_bf16(float lo, float hi) { unsigned r; asm volatile("v_cvt_pk_bf16_f32 %0, %1, %2" : "=v"(r) : "v"(lo), "v"(hi)); return r; }
; __device__ __forceinline__ float ror1(float x) { return __builtin_bit_cast(float, __builtin_amdgcn_update_dpp(0, __builtin_bit_cast(int, x), 0x121, 0xf, 0xf, false)); }
; __device__ __forceinline__ float ror2(float x) { return __builtin_bit_cast(float, __builtin_amdgcn_update_dpp(0, __builtin_bit_cast(int, x), 0x122, 0xf, 0xf, false)); }
;     __device__ __forceinline__ void operator()(AccT& acc, const Unit& u, int wr, int wc, int fr, int fq) const {
;     ...
;                 for (int m = 0; m < 4; ++m) {
;                     const int rl = ai * 128 + wr * 64 + m * 16 + fr;
;                     const f32x4 cg_ = acc[ai][0][m][n], cv_ = acc[ai][1][m][n];
;                     f32x4 p1g, p2g, p1v, p2v;
; #pragma unroll
;                     for (int j = 0; j < 4; ++j) {
;                         p1g[j] = ror1(fr == 15 ? hg[j] : cg_[j]); p2g[j] = ror2(fr >= 14 ? hg[j] : cg_[j]);
;                         p1v[j] = ror1(fr == 15 ? hv[j] : cv_[j]); p2v[j] = ror2(fr >= 14 ? hv[j] : cv_[j]);
;                     }
;                     const f32x4 hcg = bg + w0g * p2g + w1g * p1g + w2g * cg_;
;                     const f32x4 hcv = bv + w0v * p2v + w1v * p1v + w2v * cv_;
;                     const f32x2 ga = gelu_pk((f32x2){hcg[0], hcg[1]}), gb2 = gelu_pk((f32x2){hcg[2], hcg[3]});
;                     u32x2 w; w.x = cvt_pk_bf16(ga.x * hcv[0], ga.y * hcv[1]); w.y = cvt_pk_bf16(gb2.x * hcv[2], gb2.y * hcv[3]);
;                     const int t = tstart + rl;
;                     if (n == 0) stash[ai][m] = w;
;                     else if (rl >= 2) *(u32x4*)(U + (size_t)(arow0 + rl) * FF + colg0) = (u32x4){stash[ai][m].x, stash[ai][m].y, w.x, w.y};
;                     if (rl < 2 || rl >= 254) { float* hp = halo + ((size_t)u.pm * 4 + (rl < 2 ? rl : rl - 252)) * FF2; *(f32x4*)(hp + colg) = cg_; *(f32x4*)(hp + colv) = cv_; }
.Lmy_p5_7:
	s_or_b64 exec, exec, s[20:21]
	s_waitcnt lgkmcnt(0)
	s_nop 4
	v_mov_b32_dpp v214, v48 row_ror:1 row_mask:0xf bank_mask:0xf
	v_mov_b32_dpp v215, v49 row_ror:1 row_mask:0xf bank_mask:0xf
	v_mov_b32_dpp v216, v50 row_ror:1 row_mask:0xf bank_mask:0xf
	v_mov_b32_dpp v217, v51 row_ror:1 row_mask:0xf bank_mask:0xf
	s_nop 1
	v_cndmask_b32_e64 v164, v214, v164, s[48:49]
	v_cndmask_b32_e64 v165, v215, v165, s[48:49]
	v_cndmask_b32_e64 v166, v216, v166, s[48:49]
	v_cndmask_b32_e64 v167, v217, v167, s[48:49]
	v_mov_b32_dpp v214, v44 row_ror:1 row_mask:0xf bank_mask:0xf
	v_mov_b32_dpp v215, v45 row_ror:1 row_mask:0xf bank_mask:0xf
	v_mov_b32_dpp v216, v46 row_ror:1 row_mask:0xf bank_mask:0xf
	v_mov_b32_dpp v217, v47 row_ror:1 row_mask:0xf bank_mask:0xf
	s_nop 1
	v_cndmask_b32_e64 v168, v214, v168, s[48:49]
	v_cndmask_b32_e64 v169, v215, v169, s[48:49]
	v_cndmask_b32_e64 v170, v216, v170, s[48:49]
	v_cndmask_b32_e64 v171, v217, v171, s[48:49]
	v_mov_b32_dpp v214, v36 row_ror:1 row_mask:0xf bank_mask:0xf
	v_mov_b32_dpp v215, v37 row_ror:1 row_mask:0xf bank_mask:0xf
	v_mov_b32_dpp v216, v38 row_ror:1 row_mask:0xf bank_mask:0xf
	v_mov_b32_dpp v217, v39 row_ror:1 row_mask:0xf bank_mask:0xf
	s_nop 1
	v_cndmask_b32_e64 v234, v214, v234, s[48:49]
	v_cndmask_b32_e64 v235, v215, v235, s[48:49]
	v_cndmask_b32_e64 v236, v216, v236, s[48:49]
	v_cndmask_b32_e64 v237, v217, v237, s[48:49]
	v_mov_b32_dpp v214, v32 row_ror:1 row_mask:0xf bank_mask:0xf
	v_mov_b32_dpp v215, v33 row_ror:1 row_mask:0xf bank_mask:0xf
	v_mov_b32_dpp v216, v34 row_ror:1 row_mask:0xf bank_mask:0xf
	v_mov_b32_dpp v217, v35 row_ror:1 row_mask:0xf bank_mask:0xf
	s_nop 1
	v_cndmask_b32_e64 v250, v214, v250, s[48:49]
	v_cndmask_b32_e64 v251, v215, v251, s[48:49]
	v_cndmask_b32_e64 v252, v216, v252, s[48:49]
	v_cndmask_b32_e64 v253, v217, v253, s[48:49]
	v_pk_fma_f32 v[206:207], v[102:103], v[234:235], v[98:99]
	v_pk_fma_f32 v[210:211], v[92:93], v[250:251], v[84:85]
	v_pk_fma_f32 v[208:209], v[104:105], v[236:237], v[100:101]
	v_pk_fma_f32 v[212:213], v[94:95], v[252:253], v[86:87]
	v_pk_fma_f32 v[206:207], v[106:107], v[164:165], v[206:207]
	v_pk_fma_f32 v[210:211], v[88:89], v[168:169], v[210:211]
	v_pk_fma_f32 v[208:209], v[108:109], v[166:167], v[208:209]
	v_pk_fma_f32 v[212:213], v[90:91], v[170:171], v[212:213]
	v_pk_fma_f32 v[206:207], v[110:111], v[60:61], v[206:207]
	v_pk_fma_f32 v[210:211], v[80:81], v[56:57], v[210:211]
	v_pk_fma_f32 v[208:209], v[112:113], v[62:63], v[208:209]
	v_pk_fma_f32 v[212:213], v[82:83], v[58:59], v[212:213]
	v_fma_f32 v214, |v206|, s6, 1.0
	v_fma_f32 v215, |v207|, s6, 1.0
	v_pk_mul_f32 v[218:219], v[206:207], v[206:207]
	s_nop 0
	v_pk_mul_f32 v[218:219], v[218:219], s[36:37] op_sel_hi:[1,0]
	v_rcp_f32_e32 v214, v214
	v_rcp_f32_e32 v215, v215
	v_exp_f32_e32 v218, v218
	v_exp_f32_e32 v219, v219
	v_pk_fma_f32 v[216:217], v[214:215], s[24:25], v[186:187] op_sel_hi:[1,0,0]
	v_max_f32_e32 v220, 0, v206
	v_pk_fma_f32 v[216:217], v[214:215], v[216:217], s[28:29] op_sel_hi:[1,1,0]
	v_max_f32_e32 v221, 0, v207
	v_pk_fma_f32 v[216:217], v[214:215], v[216:217], s[30:31] op_sel_hi:[1,1,0]
	s_nop 0
	v_pk_fma_f32 v[216:217], v[214:215], v[216:217], s[34:35] op_sel_hi:[1,1,0]
	s_nop 0
	v_pk_mul_f32 v[216:217], v[214:215], v[216:217]
	s_nop 0
	v_pk_mul_f32 v[216:217], v[218:219], v[216:217]
	s_nop 0
	v_fma_f32 v206, -|v206|, v216, v220
	v_fma_f32 v207, -|v207|, v217, v221
	v_mul_f32_e32 v206, v210, v206
	v_mul_f32_e32 v207, v211, v207
	v_fma_f32 v214, |v208|, s6, 1.0
	v_fma_f32 v215, |v209|, s6, 1.0
	v_pk_mul_f32 v[218:219], v[208:209], v[208:209]
	s_nop 0
	v_pk_mul_f32 v[218:219], v[218:219], s[36:37] op_sel_hi:[1,0]
	v_rcp_f32_e32 v214, v214
	v_rcp_f32_e32 v215, v215
	v_exp_f32_e32 v218, v218
	v_exp_f32_e32 v219, v219
	v_pk_fma_f32 v[216:217], v[214:215], s[24:25], v[186:187] op_sel_hi:[1,0,0]
	v_max_f32_e32 v220, 0, v208
	v_pk_fma_f32 v[216:217], v[214:215], v[216:217], s[28:29] op_sel_hi:[1,1,0]
	v_max_f32_e32 v221, 0, v209
	v_pk_fma_f32 v[216:217], v[214:215], v[216:217], s[30:31] op_sel_hi:[1,1,0]
	s_nop 0
	v_pk_fma_f32 v[216:217], v[214:215], v[216:217], s[34:35] op_sel_hi:[1,1,0]
	s_nop 0
	v_pk_mul_f32 v[216:217], v[214:215], v[216:217]
	s_nop 0
	v_pk_mul_f32 v[216:217], v[218:219], v[216:217]
	s_nop 0
	v_fma_f32 v208, -|v208|, v216, v220
	v_fma_f32 v209, -|v209|, v217, v221
	v_mul_f32_e32 v208, v212, v208
	v_mul_f32_e32 v209, v213, v209
	v_mov_b64_e32 v[218:219], v[190:191]
	v_cvt_pk_bf16_f32 v220, v206, v207
	v_cvt_pk_bf16_f32 v221, v208, v209
	v_lshl_add_u64 v[126:127], s[56:57], 0, v[184:185]
	s_andn2_b64 exec, exec, s[74:75]
	global_store_dwordx4 v[126:127], v[218:221], off nt
	s_mov_b64 exec, -1
	s_and_saveexec_b64 s[22:23], s[74:75]
	s_cbranch_execz .Lmy_p5_8
	s_lshr_b32 s18, s16, 6
	s_add_i32 s18, s18, 0
	s_mul_i32 s18, s18, 0x5800
	s_mov_b32 s19, 0
	v_lshlrev_b64 v[214:215], 2, v[182:183]
	v_lshl_add_u64 v[214:215], s[18:19], 0, v[214:215]
	v_lshl_add_u64 v[214:215], s[92:93], 0, v[214:215]
	global_store_dwordx4 v[214:215], v[60:63], off offset:16 nt
	v_lshl_add_u64 v[216:217], v[214:215], 0, s[52:53]
	global_store_dwordx4 v[216:217], v[56:59], off offset:3088 nt
; __device__ __forceinline__ unsigned cvt_pk_bf16(float lo, float hi) { unsigned r; asm volatile("v_cvt_pk_bf16_f32 %0, %1, %2" : "=v"(r) : "v"(lo), "v"(hi)); return r; }
; __device__ __forceinline__ float ror1(float x) { return __builtin_bit_cast(float, __builtin_amdgcn_update_dpp(0, __builtin_bit_cast(int, x), 0x121, 0xf, 0xf, false)); }
; __device__ __forceinline__ float ror2(float x) { return __builtin_bit_cast(float, __builtin_amdgcn_update_dpp(0, __builtin_bit_cast(int, x), 0x122, 0xf, 0xf, false)); }
;     __device__ __forceinline__ void operator()(AccT& acc, const Unit& u, int wr, int wc, int fr, int fq) const {
;     ...
;                 for (int m = 0; m < 4; ++m) {
;                     const int rl = ai * 128 + wr * 64 + m * 16 + fr;
;                     const f32x4 cg_ = acc[ai][0][m][n], cv_ = acc[ai][1][m][n];
;                     f32x4 p1g, p2g, p1v, p2v;
; #pragma unroll
;                     for (int j = 0; j < 4; ++j) {
;                         p1g[j] = ror1(fr == 15 ? hg[j] : cg_[j]); p2g[j] = ror2(fr >= 14 ? hg[j] : cg_[j]);
;                         p1v[j] = ror1(fr == 15 ? hv[j] : cv_[j]); p2v[j] = ror2(fr >= 14 ? hv[j] : cv_[j]);
;                     }
;                     const f32x4 hcg = bg + w0g * p2g + w1g * p1g + w2g * cg_;
;                     const f32x4 hcv = bv + w0v * p2v + w1v * p1v + w2v * cv_;
;                     const f32x2 ga = gelu_pk((f32x2){hcg[0], hcg[1]}), gb2 = gelu_pk((f32x2){hcg[2], hcg[3]});
;                     u32x2 w; w.x = cvt_pk_bf16(ga.x * hcv[0], ga.y * hcv[1]); w.y = cvt_pk_bf16(gb2.x * hcv[2], gb2.y * hcv[3]);
;                     const int t = tstart + rl;
;                     if (n == 0) stash[ai][m] = w;
;                     else if (rl >= 2) *(u32x4*)(U + (size_t)(arow0 + rl) * FF + colg0) = (u32x4){stash[ai][m].x, stash[ai][m].y, w.x, w.y};
;                     if (rl < 2 || rl >= 254) { float* hp = halo + ((size_t)u.pm * 4 + (rl < 2 ? rl : rl - 252)) * FF2; *(f32x4*)(hp + colg) = cg_; *(f32x4*)(hp + colv) = cv_; }
.Lmy_p5_8:
	s_or_b64 exec, exec, s[22:23]
	v_pk_fma_f32 v[206:207], v[102:103], v[164:165], v[98:99]
	v_pk_fma_f32 v[210:211], v[92:93], v[168:169], v[84:85]
	v_pk_fma_f32 v[208:209], v[104:105], v[166:167], v[100:101]
	v_pk_fma_f32 v[212:213], v[94:95], v[170:171], v[86:87]
	v_pk_fma_f32 v[206:207], v[106:107], v[60:61], v[206:207]
	v_pk_fma_f32 v[210:211], v[88:89], v[56:57], v[210:211]
	v_pk_fma_f32 v[208:209], v[108:109], v[62:63], v[208:209]
	v_pk_fma_f32 v[212:213], v[90:91], v[58:59], v[212:213]
	v_pk_fma_f32 v[206:207], v[110:111], v[52:53], v[206:207]
	v_pk_fma_f32 v[210:211], v[80:81], v[40:41], v[210:211]
	v_pk_fma_f32 v[208:209], v[112:113], v[54:55], v[208:209]
	v_pk_fma_f32 v[212:213], v[82:83], v[42:43], v[212:213]
	v_fma_f32 v214, |v206|, s6, 1.0
	v_fma_f32 v215, |v207|, s6, 1.0
	v_pk_mul_f32 v[218:219], v[206:207], v[206:207]
	s_nop 0
	v_pk_mul_f32 v[218:219], v[218:219], s[36:37] op_sel_hi:[1,0]
	v_rcp_f32_e32 v214, v214
	v_rcp_f32_e32 v215, v215
	v_exp_f32_e32 v218, v218
	v_exp_f32_e32 v219, v219
	v_pk_fma_f32 v[216:217], v[214:215], s[24:25], v[186:187] op_sel_hi:[1,0,0]
	v_max_f32_e32 v220, 0, v206
	v_pk_fma_f32 v[216:217], v[214:215], v[216:217], s[28:29] op_sel_hi:[1,1,0]
	v_max_f32_e32 v221, 0, v207
	v_pk_fma_f32 v[216:217], v[214:215], v[216:217], s[30:31] op_sel_hi:[1,1,0]
	s_nop 0
	v_pk_fma_f32 v[216:217], v[214:215], v[216:217], s[34:35] op_sel_hi:[1,1,0]
	s_nop 0
	v_pk_mul_f32 v[216:217], v[214:215], v[216:217]
	s_nop 0
	v_pk_mul_f32 v[216:217], v[218:219], v[216:217]
	s_nop 0
	v_fma_f32 v206, -|v206|, v216, v220
	v_fma_f32 v207, -|v207|, v217, v221
	v_mul_f32_e32 v206, v210, v206
	v_mul_f32_e32 v207, v211, v207
	v_fma_f32 v214, |v208|, s6, 1.0
	v_fma_f32 v215, |v209|, s6, 1.0
	v_pk_mul_f32 v[218:219], v[208:209], v[208:209]
	s_nop 0
	v_pk_mul_f32 v[218:219], v[218:219], s[36:37] op_sel_hi:[1,0]
	v_rcp_f32_e32 v214, v214
	v_rcp_f32_e32 v215, v215
	v_exp_f32_e32 v218, v218
	v_exp_f32_e32 v219, v219
	v_pk_fma_f32 v[216:217], v[214:215], s[24:25], v[186:187] op_sel_hi:[1,0,0]
	v_max_f32_e32 v220, 0, v208
	v_pk_fma_f32 v[216:217], v[214:215], v[216:217], s[28:29] op_sel_hi:[1,1,0]
	v_max_f32_e32 v221, 0, v209
	v_pk_fma_f32 v[216:217], v[214:215], v[216:217], s[30:31] op_sel_hi:[1,1,0]
	s_nop 0
	v_pk_fma_f32 v[216:217], v[214:215], v[216:217], s[34:35] op_sel_hi:[1,1,0]
	s_nop 0
	v_pk_mul_f32 v[216:217], v[214:215], v[216:217]
	s_nop 0
	v_pk_mul_f32 v[216:217], v[218:219], v[216:217]
	s_nop 0
	v_fma_f32 v208, -|v208|, v216, v220
	v_fma_f32 v209, -|v209|, v217, v221
	v_mul_f32_e32 v208, v212, v208
	v_mul_f32_e32 v209, v213, v209
	v_mov_b64_e32 v[218:219], v[238:239]
	v_cvt_pk_bf16_f32 v220, v206, v207
	v_cvt_pk_bf16_f32 v221, v208, v209
	v_lshl_add_u64 v[126:127], s[58:59], 0, v[184:185]
	s_andn2_b64 exec, exec, s[74:75]
	global_store_dwordx4 v[126:127], v[218:221], off nt
	s_mov_b64 exec, -1
	s_and_saveexec_b64 s[22:23], s[74:75]
	s_cbranch_execz .Lmy_p5_9
	s_lshr_b32 s18, s16, 6
	s_add_i32 s18, s18, 1
	s_mul_i32 s18, s18, 0x5800
	s_mov_b32 s19, 0
	v_lshlrev_b64 v[214:215], 2, v[182:183]
	v_lshl_add_u64 v[214:215], s[18:19], 0, v[214:215]
	v_lshl_add_u64 v[214:215], s[92:93], 0, v[214:215]
	global_store_dwordx4 v[214:215], v[52:55], off offset:16 nt
	v_lshl_add_u64 v[216:217], v[214:215], 0, s[52:53]
	global_store_dwordx4 v[216:217], v[40:43], off offset:3088 nt
.Lmy_p5_9:
	s_or_b64 exec, exec, s[22:23]
	v_pk_fma_f32 v[206:207], v[102:103], v[60:61], v[98:99]
	v_pk_fma_f32 v[210:211], v[92:93], v[56:57], v[84:85]
	v_pk_fma_f32 v[208:209], v[104:105], v[62:63], v[100:101]
	v_pk_fma_f32 v[212:213], v[94:95], v[58:59], v[86:87]
	v_pk_fma_f32 v[206:207], v[106:107], v[52:53], v[206:207]
	v_pk_fma_f32 v[210:211], v[88:89], v[40:41], v[210:211]
	v_pk_fma_f32 v[208:209], v[108:109], v[54:55], v[208:209]
	v_pk_fma_f32 v[212:213], v[90:91], v[42:43], v[212:213]
	v_pk_fma_f32 v[206:207], v[110:111], v[36:37], v[206:207]
	v_pk_fma_f32 v[210:211], v[80:81], v[32:33], v[210:211]
	v_pk_fma_f32 v[208:209], v[112:113], v[38:39], v[208:209]
	v_pk_fma_f32 v[212:213], v[82:83], v[34:35], v[212:213]
	v_fma_f32 v214, |v206|, s6, 1.0
	v_fma_f32 v215, |v207|, s6, 1.0
	v_pk_mul_f32 v[218:219], v[206:207], v[206:207]
	s_nop 0
	v_pk_mul_f32 v[218:219], v[218:219], s[36:37] op_sel_hi:[1,0]
	v_rcp_f32_e32 v214, v214
	v_rcp_f32_e32 v215, v215
	v_exp_f32_e32 v218, v218
	v_exp_f32_e32 v219, v219
	v_pk_fma_f32 v[216:217], v[214:215], s[24:25], v[186:187] op_sel_hi:[1,0,0]
	v_max_f32_e32 v220, 0, v206
	v_pk_fma_f32 v[216:217], v[214:215], v[216:217], s[28:29] op_sel_hi:[1,1,0]
	v_max_f32_e32 v221, 0, v207
	v_pk_fma_f32 v[216:217], v[214:215], v[216:217], s[30:31] op_sel_hi:[1,1,0]
	s_nop 0
	v_pk_fma_f32 v[216:217], v[214:215], v[216:217], s[34:35] op_sel_hi:[1,1,0]
	s_nop 0
	v_pk_mul_f32 v[216:217], v[214:215], v[216:217]
	s_nop 0
	v_pk_mul_f32 v[216:217], v[218:219], v[216:217]
	s_nop 0
	v_fma_f32 v206, -|v206|, v216, v220
	v_fma_f32 v207, -|v207|, v217, v221
	v_mul_f32_e32 v206, v210, v206
	v_mul_f32_e32 v207, v211, v207
	v_fma_f32 v214, |v208|, s6, 1.0
	v_fma_f32 v215, |v209|, s6, 1.0
	v_pk_mul_f32 v[218:219], v[208:209], v[208:209]
	s_nop 0
	v_pk_mul_f32 v[218:219], v[218:219], s[36:37] op_sel_hi:[1,0]
	v_rcp_f32_e32 v214, v214
	v_rcp_f32_e32 v215, v215
	v_exp_f32_e32 v218, v218
	v_exp_f32_e32 v219, v219
	v_pk_fma_f32 v[216:217], v[214:215], s[24:25], v[186:187] op_sel_hi:[1,0,0]
	v_max_f32_e32 v220, 0, v208
	v_pk_fma_f32 v[216:217], v[214:215], v[216:217], s[28:29] op_sel_hi:[1,1,0]
	v_max_f32_e32 v221, 0, v209
	v_pk_fma_f32 v[216:217], v[214:215], v[216:217], s[30:31] op_sel_hi:[1,1,0]
	s_nop 0
	v_pk_fma_f32 v[216:217], v[214:215], v[216:217], s[34:35] op_sel_hi:[1,1,0]
; #define LAS __attribute__((address_space(3)))
; __device__ __forceinline__ unsigned cvt_pk_bf16(float lo, float hi) { unsigned r; asm volatile("v_cvt_pk_bf16_f32 %0, %1, %2" : "=v"(r) : "v"(lo), "v"(hi)); return r; }
; __device__ __forceinline__ float ror1(float x) { return __builtin_bit_cast(float, __builtin_amdgcn_update_dpp(0, __builtin_bit_cast(int, x), 0x121, 0xf, 0xf, false)); }
; __device__ __forceinline__ float ror2(float x) { return __builtin_bit_cast(float, __builtin_amdgcn_update_dpp(0, __builtin_bit_cast(int, x), 0x122, 0xf, 0xf, false)); }
;     __device__ __forceinline__ void operator()(AccT& acc, const Unit& u, int wr, int wc, int fr, int fq) const {
;     ...
;             for (int ai = 0; ai < 2; ++ai) {
;                 f32x4 hg = (f32x4){0.f, 0.f, 0.f, 0.f}, hv = hg;
;                 const int s = ai * 2 + wr;
;                 if (s > 0 && fr >= 14) {
;                     hg = *(const LAS f32x4*)(xch + (((s - 1) * 2 + (fr - 14)) * 256 + wc * 32 + fq * 8 + n * 4));
;                     hv = *(const LAS f32x4*)(xch + (((s - 1) * 2 + (fr - 14)) * 256 + 128 + wc * 32 + fq * 8 + n * 4));
;                 }
; #pragma unroll
;                 for (int m = 0; m < 4; ++m) {
;                     const int rl = ai * 128 + wr * 64 + m * 16 + fr;
;                     const f32x4 cg_ = acc[ai][0][m][n], cv_ = acc[ai][1][m][n];
;                     f32x4 p1g, p2g, p1v, p2v;
; #pragma unroll
;                     for (int j = 0; j < 4; ++j) {
;                         p1g[j] = ror1(fr == 15 ? hg[j] : cg_[j]); p2g[j] = ror2(fr >= 14 ? hg[j] : cg_[j]);
;                         p1v[j] = ror1(fr == 15 ? hv[j] : cv_[j]); p2v[j] = ror2(fr >= 14 ? hv[j] : cv_[j]);
;                     }
;                     const f32x4 hcg = bg + w0g * p2g + w1g * p1g + w2g * cg_;
;                     const f32x4 hcv = bv + w0v * p2v + w1v * p1v + w2v * cv_;
;                     const f32x2 ga = gelu_pk((f32x2){hcg[0], hcg[1]}), gb2 = gelu_pk((f32x2){hcg[2], hcg[3]});
;                     u32x2 w; w.x = cvt_pk_bf16(ga.x * hcv[0], ga.y * hcv[1]); w.y = cvt_pk_bf16(gb2.x * hcv[2], gb2.y * hcv[3]);
;                     const int t = tstart + rl;
;                     if (n == 0) stash[ai][m] = w;
;                     else if (rl >= 2) *(u32x4*)(U + (size_t)(arow0 + rl) * FF + colg0) = (u32x4){stash[ai][m].x, stash[ai][m].y, w.x, w.y};
	s_nop 0
	v_pk_mul_f32 v[216:217], v[214:215], v[216:217]
	s_nop 0
	v_pk_mul_f32 v[216:217], v[218:219], v[216:217]
	s_nop 0
	v_fma_f32 v208, -|v208|, v216, v220
	v_fma_f32 v209, -|v209|, v217, v221
	v_mul_f32_e32 v208, v212, v208
	v_mul_f32_e32 v209, v213, v209
	v_mov_b64_e32 v[218:219], v[160:161]
	v_cvt_pk_bf16_f32 v220, v206, v207
	v_cvt_pk_bf16_f32 v221, v208, v209
	v_lshl_add_u64 v[126:127], s[60:61], 0, v[184:185]
	global_store_dwordx4 v[126:127], v[218:221], off nt
	v_pk_fma_f32 v[206:207], v[102:103], v[52:53], v[98:99]
	v_pk_fma_f32 v[210:211], v[92:93], v[40:41], v[84:85]
	v_pk_fma_f32 v[208:209], v[104:105], v[54:55], v[100:101]
	v_pk_fma_f32 v[212:213], v[94:95], v[42:43], v[86:87]
	v_pk_fma_f32 v[206:207], v[106:107], v[36:37], v[206:207]
	v_pk_fma_f32 v[210:211], v[88:89], v[32:33], v[210:211]
	v_pk_fma_f32 v[208:209], v[108:109], v[38:39], v[208:209]
	v_pk_fma_f32 v[212:213], v[90:91], v[34:35], v[212:213]
	v_pk_fma_f32 v[206:207], v[110:111], v[48:49], v[206:207]
	v_pk_fma_f32 v[210:211], v[80:81], v[44:45], v[210:211]
	v_pk_fma_f32 v[208:209], v[112:113], v[50:51], v[208:209]
	v_pk_fma_f32 v[212:213], v[82:83], v[46:47], v[212:213]
	v_fma_f32 v214, |v206|, s6, 1.0
	v_fma_f32 v215, |v207|, s6, 1.0
	v_pk_mul_f32 v[218:219], v[206:207], v[206:207]
	s_nop 0
	v_pk_mul_f32 v[218:219], v[218:219], s[36:37] op_sel_hi:[1,0]
	v_rcp_f32_e32 v214, v214
	v_rcp_f32_e32 v215, v215
	v_exp_f32_e32 v218, v218
	v_exp_f32_e32 v219, v219
	v_pk_fma_f32 v[216:217], v[214:215], s[24:25], v[186:187] op_sel_hi:[1,0,0]
	v_max_f32_e32 v220, 0, v206
	v_pk_fma_f32 v[216:217], v[214:215], v[216:217], s[28:29] op_sel_hi:[1,1,0]
	v_max_f32_e32 v221, 0, v207
	v_pk_fma_f32 v[216:217], v[214:215], v[216:217], s[30:31] op_sel_hi:[1,1,0]
	s_nop 0
	v_pk_fma_f32 v[216:217], v[214:215], v[216:217], s[34:35] op_sel_hi:[1,1,0]
	s_nop 0
	v_pk_mul_f32 v[216:217], v[214:215], v[216:217]
	s_nop 0
	v_pk_mul_f32 v[216:217], v[218:219], v[216:217]
	s_nop 0
	v_fma_f32 v206, -|v206|, v216, v220
	v_fma_f32 v207, -|v207|, v217, v221
	v_mul_f32_e32 v206, v210, v206
	v_mul_f32_e32 v207, v211, v207
	v_fma_f32 v214, |v208|, s6, 1.0
	v_fma_f32 v215, |v209|, s6, 1.0
	v_pk_mul_f32 v[218:219], v[208:209], v[208:209]
	s_nop 0
	v_pk_mul_f32 v[218:219], v[218:219], s[36:37] op_sel_hi:[1,0]
	v_rcp_f32_e32 v214, v214
	v_rcp_f32_e32 v215, v215
	v_exp_f32_e32 v218, v218
	v_exp_f32_e32 v219, v219
	v_pk_fma_f32 v[216:217], v[214:215], s[24:25], v[186:187] op_sel_hi:[1,0,0]
	v_max_f32_e32 v220, 0, v208
	v_pk_fma_f32 v[216:217], v[214:215], v[216:217], s[28:29] op_sel_hi:[1,1,0]
	v_max_f32_e32 v221, 0, v209
	v_pk_fma_f32 v[216:217], v[214:215], v[216:217], s[30:31] op_sel_hi:[1,1,0]
	s_nop 0
	v_pk_fma_f32 v[216:217], v[214:215], v[216:217], s[34:35] op_sel_hi:[1,1,0]
	s_nop 0
	v_pk_mul_f32 v[216:217], v[214:215], v[216:217]
	s_nop 0
	v_pk_mul_f32 v[216:217], v[218:219], v[216:217]
	s_nop 0
	v_fma_f32 v208, -|v208|, v216, v220
	v_fma_f32 v209, -|v209|, v217, v221
	v_mul_f32_e32 v208, v212, v208
	v_mul_f32_e32 v209, v213, v209
	v_mov_b64_e32 v[218:219], v[144:145]
	v_cvt_pk_bf16_f32 v220, v206, v207
	v_cvt_pk_bf16_f32 v221, v208, v209
	v_lshl_add_u64 v[126:127], s[62:63], 0, v[184:185]
	global_store_dwordx4 v[126:127], v[218:221], off nt
	v_mov_b64_e32 v[164:165], 0
	v_mov_b64_e32 v[166:167], 0
	v_mov_b64_e32 v[168:169], 0
	v_mov_b64_e32 v[170:171], 0
	v_mov_b64_e32 v[234:235], 0
	v_mov_b64_e32 v[236:237], 0
	v_mov_b64_e32 v[250:251], 0
	v_mov_b64_e32 v[252:253], 0
	s_and_saveexec_b64 s[20:21], s[48:49]
	s_cbranch_execz .Lmy_p5_10
	ds_read_b128 v[234:237], v188 offset:4128
	ds_read_b128 v[250:253], v188 offset:4144
	ds_read_b128 v[164:167], v188 offset:4192
	ds_read_b128 v[168:171], v188 offset:4208
.Lmy_p5_10:
	s_or_b64 exec, exec, s[20:21]
	s_waitcnt lgkmcnt(0)
	s_nop 4
	v_mov_b32_dpp v214, v16 row_ror:1 row_mask:0xf bank_mask:0xf
	v_mov_b32_dpp v215, v17 row_ror:1 row_mask:0xf bank_mask:0xf
	v_mov_b32_dpp v216, v18 row_ror:1 row_mask:0xf bank_mask:0xf
	v_mov_b32_dpp v217, v19 row_ror:1 row_mask:0xf bank_mask:0xf
	s_nop 1
	v_cndmask_b32_e64 v164, v214, v164, s[48:49]
	v_cndmask_b32_e64 v165, v215, v165, s[48:49]
	v_cndmask_b32_e64 v166, v216, v166, s[48:49]
	v_cndmask_b32_e64 v167, v217, v167, s[48:49]
	v_mov_b32_dpp v214, v20 row_ror:1 row_mask:0xf bank_mask:0xf
	v_mov_b32_dpp v215, v21 row_ror:1 row_mask:0xf bank_mask:0xf
	v_mov_b32_dpp v216, v22 row_ror:1 row_mask:0xf bank_mask:0xf
	v_mov_b32_dpp v217, v23 row_ror:1 row_mask:0xf bank_mask:0xf
	s_nop 1
	v_cndmask_b32_e64 v168, v214, v168, s[48:49]
	v_cndmask_b32_e64 v169, v215, v169, s[48:49]
	v_cndmask_b32_e64 v170, v216, v170, s[48:49]
	v_cndmask_b32_e64 v171, v217, v171, s[48:49]
	v_mov_b32_dpp v214, v4 row_ror:1 row_mask:0xf bank_mask:0xf
	v_mov_b32_dpp v215, v5 row_ror:1 row_mask:0xf bank_mask:0xf
	v_mov_b32_dpp v216, v6 row_ror:1 row_mask:0xf bank_mask:0xf
	v_mov_b32_dpp v217, v7 row_ror:1 row_mask:0xf bank_mask:0xf
	s_nop 1
	v_cndmask_b32_e64 v234, v214, v234, s[48:49]
	v_cndmask_b32_e64 v235, v215, v235, s[48:49]
	v_cndmask_b32_e64 v236, v216, v236, s[48:49]
	v_cndmask_b32_e64 v237, v217, v237, s[48:49]
	v_mov_b32_dpp v214, v0 row_ror:1 row_mask:0xf bank_mask:0xf
	v_mov_b32_dpp v215, v1 row_ror:1 row_mask:0xf bank_mask:0xf
	v_mov_b32_dpp v216, v2 row_ror:1 row_mask:0xf bank_mask:0xf
	v_mov_b32_dpp v217, v3 row_ror:1 row_mask:0xf bank_mask:0xf
	s_nop 1
	v_cndmask_b32_e64 v250, v214, v250, s[48:49]
	v_cndmask_b32_e64 v251, v215, v251, s[48:49]
	v_cndmask_b32_e64 v252, v216, v252, s[48:49]
	v_cndmask_b32_e64 v253, v217, v253, s[48:49]
	v_pk_fma_f32 v[206:207], v[102:103], v[234:235], v[98:99]
	v_pk_fma_f32 v[210:211], v[92:93], v[250:251], v[84:85]
; __device__ __forceinline__ unsigned cvt_pk_bf16(float lo, float hi) { unsigned r; asm volatile("v_cvt_pk_bf16_f32 %0, %1, %2" : "=v"(r) : "v"(lo), "v"(hi)); return r; }
; __device__ __forceinline__ float ror1(float x) { return __builtin_bit_cast(float, __builtin_amdgcn_update_dpp(0, __builtin_bit_cast(int, x), 0x121, 0xf, 0xf, false)); }
; __device__ __forceinline__ float ror2(float x) { return __builtin_bit_cast(float, __builtin_amdgcn_update_dpp(0, __builtin_bit_cast(int, x), 0x122, 0xf, 0xf, false)); }
;     __device__ __forceinline__ void operator()(AccT& acc, const Unit& u, int wr, int wc, int fr, int fq) const {
;     ...
;                 for (int m = 0; m < 4; ++m) {
;                     const int rl = ai * 128 + wr * 64 + m * 16 + fr;
;                     const f32x4 cg_ = acc[ai][0][m][n], cv_ = acc[ai][1][m][n];
;                     f32x4 p1g, p2g, p1v, p2v;
; #pragma unroll
;                     for (int j = 0; j < 4; ++j) {
;                         p1g[j] = ror1(fr == 15 ? hg[j] : cg_[j]); p2g[j] = ror2(fr >= 14 ? hg[j] : cg_[j]);
;                         p1v[j] = ror1(fr == 15 ? hv[j] : cv_[j]); p2v[j] = ror2(fr >= 14 ? hv[j] : cv_[j]);
;                     }
;                     const f32x4 hcg = bg + w0g * p2g + w1g * p1g + w2g * cg_;
;                     const f32x4 hcv = bv + w0v * p2v + w1v * p1v + w2v * cv_;
;                     const f32x2 ga = gelu_pk((f32x2){hcg[0], hcg[1]}), gb2 = gelu_pk((f32x2){hcg[2], hcg[3]});
;                     u32x2 w; w.x = cvt_pk_bf16(ga.x * hcv[0], ga.y * hcv[1]); w.y = cvt_pk_bf16(gb2.x * hcv[2], gb2.y * hcv[3]);
;                     const int t = tstart + rl;
;                     if (n == 0) stash[ai][m] = w;
;                     else if (rl >= 2) *(u32x4*)(U + (size_t)(arow0 + rl) * FF + colg0) = (u32x4){stash[ai][m].x, stash[ai][m].y, w.x, w.y};
	v_pk_fma_f32 v[208:209], v[104:105], v[236:237], v[100:101]
	v_pk_fma_f32 v[212:213], v[94:95], v[252:253], v[86:87]
	v_pk_fma_f32 v[206:207], v[106:107], v[164:165], v[206:207]
	v_pk_fma_f32 v[210:211], v[88:89], v[168:169], v[210:211]
	v_pk_fma_f32 v[208:209], v[108:109], v[166:167], v[208:209]
	v_pk_fma_f32 v[212:213], v[90:91], v[170:171], v[212:213]
	v_pk_fma_f32 v[206:207], v[110:111], v[28:29], v[206:207]
	v_pk_fma_f32 v[210:211], v[80:81], v[24:25], v[210:211]
	v_pk_fma_f32 v[208:209], v[112:113], v[30:31], v[208:209]
	v_pk_fma_f32 v[212:213], v[82:83], v[26:27], v[212:213]
	v_fma_f32 v214, |v206|, s6, 1.0
	v_fma_f32 v215, |v207|, s6, 1.0
	v_pk_mul_f32 v[218:219], v[206:207], v[206:207]
	s_nop 0
	v_pk_mul_f32 v[218:219], v[218:219], s[36:37] op_sel_hi:[1,0]
	v_rcp_f32_e32 v214, v214
	v_rcp_f32_e32 v215, v215
	v_exp_f32_e32 v218, v218
	v_exp_f32_e32 v219, v219
	v_pk_fma_f32 v[216:217], v[214:215], s[24:25], v[186:187] op_sel_hi:[1,0,0]
	v_max_f32_e32 v220, 0, v206
	v_pk_fma_f32 v[216:217], v[214:215], v[216:217], s[28:29] op_sel_hi:[1,1,0]
	v_max_f32_e32 v221, 0, v207
	v_pk_fma_f32 v[216:217], v[214:215], v[216:217], s[30:31] op_sel_hi:[1,1,0]
	s_nop 0
	v_pk_fma_f32 v[216:217], v[214:215], v[216:217], s[34:35] op_sel_hi:[1,1,0]
	s_nop 0
	v_pk_mul_f32 v[216:217], v[214:215], v[216:217]
	s_nop 0
	v_pk_mul_f32 v[216:217], v[218:219], v[216:217]
	s_nop 0
	v_fma_f32 v206, -|v206|, v216, v220
	v_fma_f32 v207, -|v207|, v217, v221
	v_mul_f32_e32 v206, v210, v206
	v_mul_f32_e32 v207, v211, v207
	v_fma_f32 v214, |v208|, s6, 1.0
	v_fma_f32 v215, |v209|, s6, 1.0
	v_pk_mul_f32 v[218:219], v[208:209], v[208:209]
	s_nop 0
	v_pk_mul_f32 v[218:219], v[218:219], s[36:37] op_sel_hi:[1,0]
	v_rcp_f32_e32 v214, v214
	v_rcp_f32_e32 v215, v215
	v_exp_f32_e32 v218, v218
	v_exp_f32_e32 v219, v219
	v_pk_fma_f32 v[216:217], v[214:215], s[24:25], v[186:187] op_sel_hi:[1,0,0]
	v_max_f32_e32 v220, 0, v208
	v_pk_fma_f32 v[216:217], v[214:215], v[216:217], s[28:29] op_sel_hi:[1,1,0]
	v_max_f32_e32 v221, 0, v209
	v_pk_fma_f32 v[216:217], v[214:215], v[216:217], s[30:31] op_sel_hi:[1,1,0]
	s_nop 0
	v_pk_fma_f32 v[216:217], v[214:215], v[216:217], s[34:35] op_sel_hi:[1,1,0]
	s_nop 0
	v_pk_mul_f32 v[216:217], v[214:215], v[216:217]
	s_nop 0
	v_pk_mul_f32 v[216:217], v[218:219], v[216:217]
	s_nop 0
	v_fma_f32 v208, -|v208|, v216, v220
	v_fma_f32 v209, -|v209|, v217, v221
	v_mul_f32_e32 v208, v212, v208
	v_mul_f32_e32 v209, v213, v209
	v_mov_b64_e32 v[218:219], v[156:157]
	v_cvt_pk_bf16_f32 v220, v206, v207
	v_cvt_pk_bf16_f32 v221, v208, v209
	v_lshl_add_u64 v[126:127], s[64:65], 0, v[184:185]
	global_store_dwordx4 v[126:127], v[218:221], off nt
	v_pk_fma_f32 v[206:207], v[102:103], v[164:165], v[98:99]
	v_pk_fma_f32 v[210:211], v[92:93], v[168:169], v[84:85]
	v_pk_fma_f32 v[208:209], v[104:105], v[166:167], v[100:101]
	v_pk_fma_f32 v[212:213], v[94:95], v[170:171], v[86:87]
	v_pk_fma_f32 v[206:207], v[106:107], v[28:29], v[206:207]
	v_pk_fma_f32 v[210:211], v[88:89], v[24:25], v[210:211]
	v_pk_fma_f32 v[208:209], v[108:109], v[30:31], v[208:209]
	v_pk_fma_f32 v[212:213], v[90:91], v[26:27], v[212:213]
	v_pk_fma_f32 v[206:207], v[110:111], v[12:13], v[206:207]
	v_pk_fma_f32 v[210:211], v[80:81], v[8:9], v[210:211]
	v_pk_fma_f32 v[208:209], v[112:113], v[14:15], v[208:209]
	v_pk_fma_f32 v[212:213], v[82:83], v[10:11], v[212:213]
	v_fma_f32 v214, |v206|, s6, 1.0
	v_fma_f32 v215, |v207|, s6, 1.0
	v_pk_mul_f32 v[218:219], v[206:207], v[206:207]
	s_nop 0
	v_pk_mul_f32 v[218:219], v[218:219], s[36:37] op_sel_hi:[1,0]
	v_rcp_f32_e32 v214, v214
	v_rcp_f32_e32 v215, v215
	v_exp_f32_e32 v218, v218
	v_exp_f32_e32 v219, v219
	v_pk_fma_f32 v[216:217], v[214:215], s[24:25], v[186:187] op_sel_hi:[1,0,0]
	v_max_f32_e32 v220, 0, v206
	v_pk_fma_f32 v[216:217], v[214:215], v[216:217], s[28:29] op_sel_hi:[1,1,0]
	v_max_f32_e32 v221, 0, v207
	v_pk_fma_f32 v[216:217], v[214:215], v[216:217], s[30:31] op_sel_hi:[1,1,0]
	s_nop 0
	v_pk_fma_f32 v[216:217], v[214:215], v[216:217], s[34:35] op_sel_hi:[1,1,0]
	s_nop 0
	v_pk_mul_f32 v[216:217], v[214:215], v[216:217]
	s_nop 0
	v_pk_mul_f32 v[216:217], v[218:219], v[216:217]
	s_nop 0
	v_fma_f32 v206, -|v206|, v216, v220
	v_fma_f32 v207, -|v207|, v217, v221
	v_mul_f32_e32 v206, v210, v206
	v_mul_f32_e32 v207, v211, v207
	v_fma_f32 v214, |v208|, s6, 1.0
	v_fma_f32 v215, |v209|, s6, 1.0
	v_pk_mul_f32 v[218:219], v[208:209], v[208:209]
	s_nop 0
	v_pk_mul_f32 v[218:219], v[218:219], s[36:37] op_sel_hi:[1,0]
	v_rcp_f32_e32 v214, v214
	v_rcp_f32_e32 v215, v215
	v_exp_f32_e32 v218, v218
	v_exp_f32_e32 v219, v219
	v_pk_fma_f32 v[216:217], v[214:215], s[24:25], v[186:187] op_sel_hi:[1,0,0]
	v_max_f32_e32 v220, 0, v208
	v_pk_fma_f32 v[216:217], v[214:215], v[216:217], s[28:29] op_sel_hi:[1,1,0]
	v_max_f32_e32 v221, 0, v209
	v_pk_fma_f32 v[216:217], v[214:215], v[216:217], s[30:31] op_sel_hi:[1,1,0]
	s_nop 0
	v_pk_fma_f32 v[216:217], v[214:215], v[216:217], s[34:35] op_sel_hi:[1,1,0]
	s_nop 0
	v_pk_mul_f32 v[216:217], v[214:215], v[216:217]
	s_nop 0
	v_pk_mul_f32 v[216:217], v[218:219], v[216:217]
	s_nop 0
	v_fma_f32 v208, -|v208|, v216, v220
	v_fma_f32 v209, -|v209|, v217, v221
	v_mul_f32_e32 v208, v212, v208
	v_mul_f32_e32 v209, v213, v209
	v_mov_b64_e32 v[218:219], v[118:119]
	v_cvt_pk_bf16_f32 v220, v206, v207
	v_cvt_pk_bf16_f32 v221, v208, v209
	v_lshl_add_u64 v[126:127], s[66:67], 0, v[184:185]
	global_store_dwordx4 v[126:127], v[218:221], off nt
	v_pk_fma_f32 v[206:207], v[102:103], v[28:29], v[98:99]
	v_pk_fma_f32 v[210:211], v[92:93], v[24:25], v[84:85]
	v_pk_fma_f32 v[208:209], v[104:105], v[30:31], v[100:101]
	v_pk_fma_f32 v[212:213], v[94:95], v[26:27], v[86:87]
; __device__ __forceinline__ unsigned cvt_pk_bf16(float lo, float hi) { unsigned r; asm volatile("v_cvt_pk_bf16_f32 %0, %1, %2" : "=v"(r) : "v"(lo), "v"(hi)); return r; }
; __device__ __forceinline__ float ror1(float x) { return __builtin_bit_cast(float, __builtin_amdgcn_update_dpp(0, __builtin_bit_cast(int, x), 0x121, 0xf, 0xf, false)); }
; __device__ __forceinline__ float ror2(float x) { return __builtin_bit_cast(float, __builtin_amdgcn_update_dpp(0, __builtin_bit_cast(int, x), 0x122, 0xf, 0xf, false)); }
;     __device__ __forceinline__ void operator()(AccT& acc, const Unit& u, int wr, int wc, int fr, int fq) const {
;     ...
;                 for (int m = 0; m < 4; ++m) {
;                     const int rl = ai * 128 + wr * 64 + m * 16 + fr;
;                     const f32x4 cg_ = acc[ai][0][m][n], cv_ = acc[ai][1][m][n];
;                     f32x4 p1g, p2g, p1v, p2v;
; #pragma unroll
;                     for (int j = 0; j < 4; ++j) {
;                         p1g[j] = ror1(fr == 15 ? hg[j] : cg_[j]); p2g[j] = ror2(fr >= 14 ? hg[j] : cg_[j]);
;                         p1v[j] = ror1(fr == 15 ? hv[j] : cv_[j]); p2v[j] = ror2(fr >= 14 ? hv[j] : cv_[j]);
;                     }
;                     const f32x4 hcg = bg + w0g * p2g + w1g * p1g + w2g * cg_;
;                     const f32x4 hcv = bv + w0v * p2v + w1v * p1v + w2v * cv_;
;                     const f32x2 ga = gelu_pk((f32x2){hcg[0], hcg[1]}), gb2 = gelu_pk((f32x2){hcg[2], hcg[3]});
;                     u32x2 w; w.x = cvt_pk_bf16(ga.x * hcv[0], ga.y * hcv[1]); w.y = cvt_pk_bf16(gb2.x * hcv[2], gb2.y * hcv[3]);
;                     const int t = tstart + rl;
;                     if (n == 0) stash[ai][m] = w;
;                     else if (rl >= 2) *(u32x4*)(U + (size_t)(arow0 + rl) * FF + colg0) = (u32x4){stash[ai][m].x, stash[ai][m].y, w.x, w.y};
;                     if (rl < 2 || rl >= 254) { float* hp = halo + ((size_t)u.pm * 4 + (rl < 2 ? rl : rl - 252)) * FF2; *(f32x4*)(hp + colg) = cg_; *(f32x4*)(hp + colv) = cv_; }
;                     if (t >= SEQ - 2) { float* cp = conv_p + (size_t)(b * 2 + (t - (SEQ - 2))) * FF2; *(f32x4*)(cp + colg) = cg_; *(f32x4*)(cp + colv) = cv_; }
	v_pk_fma_f32 v[206:207], v[106:107], v[12:13], v[206:207]
	v_pk_fma_f32 v[210:211], v[88:89], v[8:9], v[210:211]
	v_pk_fma_f32 v[208:209], v[108:109], v[14:15], v[208:209]
	v_pk_fma_f32 v[212:213], v[90:91], v[10:11], v[212:213]
	v_pk_fma_f32 v[206:207], v[110:111], v[4:5], v[206:207]
	v_pk_fma_f32 v[210:211], v[80:81], v[0:1], v[210:211]
	v_pk_fma_f32 v[208:209], v[112:113], v[6:7], v[208:209]
	v_pk_fma_f32 v[212:213], v[82:83], v[2:3], v[212:213]
	v_fma_f32 v214, |v206|, s6, 1.0
	v_fma_f32 v215, |v207|, s6, 1.0
	v_pk_mul_f32 v[218:219], v[206:207], v[206:207]
	s_nop 0
	v_pk_mul_f32 v[218:219], v[218:219], s[36:37] op_sel_hi:[1,0]
	v_rcp_f32_e32 v214, v214
	v_rcp_f32_e32 v215, v215
	v_exp_f32_e32 v218, v218
	v_exp_f32_e32 v219, v219
	v_pk_fma_f32 v[216:217], v[214:215], s[24:25], v[186:187] op_sel_hi:[1,0,0]
	v_max_f32_e32 v220, 0, v206
	v_pk_fma_f32 v[216:217], v[214:215], v[216:217], s[28:29] op_sel_hi:[1,1,0]
	v_max_f32_e32 v221, 0, v207
	v_pk_fma_f32 v[216:217], v[214:215], v[216:217], s[30:31] op_sel_hi:[1,1,0]
	s_nop 0
	v_pk_fma_f32 v[216:217], v[214:215], v[216:217], s[34:35] op_sel_hi:[1,1,0]
	s_nop 0
	v_pk_mul_f32 v[216:217], v[214:215], v[216:217]
	s_nop 0
	v_pk_mul_f32 v[216:217], v[218:219], v[216:217]
	s_nop 0
	v_fma_f32 v206, -|v206|, v216, v220
	v_fma_f32 v207, -|v207|, v217, v221
	v_mul_f32_e32 v206, v210, v206
	v_mul_f32_e32 v207, v211, v207
	v_fma_f32 v214, |v208|, s6, 1.0
	v_fma_f32 v215, |v209|, s6, 1.0
	v_pk_mul_f32 v[218:219], v[208:209], v[208:209]
	s_nop 0
	v_pk_mul_f32 v[218:219], v[218:219], s[36:37] op_sel_hi:[1,0]
	v_rcp_f32_e32 v214, v214
	v_rcp_f32_e32 v215, v215
	v_exp_f32_e32 v218, v218
	v_exp_f32_e32 v219, v219
	v_pk_fma_f32 v[216:217], v[214:215], s[24:25], v[186:187] op_sel_hi:[1,0,0]
	v_max_f32_e32 v220, 0, v208
	v_pk_fma_f32 v[216:217], v[214:215], v[216:217], s[28:29] op_sel_hi:[1,1,0]
	v_max_f32_e32 v221, 0, v209
	v_pk_fma_f32 v[216:217], v[214:215], v[216:217], s[30:31] op_sel_hi:[1,1,0]
	s_nop 0
	v_pk_fma_f32 v[216:217], v[214:215], v[216:217], s[34:35] op_sel_hi:[1,1,0]
	s_nop 0
	v_pk_mul_f32 v[216:217], v[214:215], v[216:217]
	s_nop 0
	v_pk_mul_f32 v[216:217], v[218:219], v[216:217]
	s_nop 0
	v_fma_f32 v208, -|v208|, v216, v220
	v_fma_f32 v209, -|v209|, v217, v221
	v_mul_f32_e32 v208, v212, v208
	v_mul_f32_e32 v209, v213, v209
	v_mov_b64_e32 v[218:219], v[140:141]
	v_cvt_pk_bf16_f32 v220, v206, v207
	v_cvt_pk_bf16_f32 v221, v208, v209
	v_lshl_add_u64 v[126:127], s[68:69], 0, v[184:185]
	global_store_dwordx4 v[126:127], v[218:221], off nt
	s_and_saveexec_b64 s[22:23], s[76:77]
	s_cbranch_execz .Lmy_p5_11
	s_lshr_b32 s18, s16, 6
	s_add_i32 s18, s18, 2
	s_mul_i32 s18, s18, 0x5800
	s_mov_b32 s19, 0
	v_lshlrev_b64 v[214:215], 2, v[182:183]
	v_lshl_add_u64 v[214:215], s[18:19], 0, v[214:215]
	v_lshl_add_u64 v[214:215], s[92:93], 0, v[214:215]
	global_store_dwordx4 v[214:215], v[4:7], off offset:16 nt
	v_lshl_add_u64 v[216:217], v[214:215], 0, s[52:53]
	global_store_dwordx4 v[216:217], v[0:3], off offset:3088 nt
	s_bfe_u32 s18, s16, 0x60008
	s_cmp_eq_u32 s18, 63
	s_cbranch_scc0 .Lmy_p5_11
	s_lshr_b32 s18, s16, 14
	s_lshl_b32 s18, s18, 1
	s_add_i32 s18, s18, 0
	s_mul_i32 s18, s18, 0x5800
	s_mov_b32 s19, 0
	v_lshlrev_b64 v[214:215], 2, v[182:183]
	v_lshl_add_u64 v[214:215], s[18:19], 0, v[214:215]
	v_lshl_add_u64 v[214:215], s[0:1], 0, v[214:215]
	global_store_dwordx4 v[214:215], v[4:7], off offset:16 nt
	v_lshl_add_u64 v[216:217], v[214:215], 0, s[52:53]
	global_store_dwordx4 v[216:217], v[0:3], off offset:3088 nt
; __device__ __forceinline__ unsigned cvt_pk_bf16(float lo, float hi) { unsigned r; asm volatile("v_cvt_pk_bf16_f32 %0, %1, %2" : "=v"(r) : "v"(lo), "v"(hi)); return r; }
; __device__ __forceinline__ float ror1(float x) { return __builtin_bit_cast(float, __builtin_amdgcn_update_dpp(0, __builtin_bit_cast(int, x), 0x121, 0xf, 0xf, false)); }
; __device__ __forceinline__ float ror2(float x) { return __builtin_bit_cast(float, __builtin_amdgcn_update_dpp(0, __builtin_bit_cast(int, x), 0x122, 0xf, 0xf, false)); }
;     __device__ __forceinline__ void operator()(AccT& acc, const Unit& u, int wr, int wc, int fr, int fq) const {
;     ...
;                 for (int m = 0; m < 4; ++m) {
;                     const int rl = ai * 128 + wr * 64 + m * 16 + fr;
;                     const f32x4 cg_ = acc[ai][0][m][n], cv_ = acc[ai][1][m][n];
;                     f32x4 p1g, p2g, p1v, p2v;
; #pragma unroll
;                     for (int j = 0; j < 4; ++j) {
;                         p1g[j] = ror1(fr == 15 ? hg[j] : cg_[j]); p2g[j] = ror2(fr >= 14 ? hg[j] : cg_[j]);
;                         p1v[j] = ror1(fr == 15 ? hv[j] : cv_[j]); p2v[j] = ror2(fr >= 14 ? hv[j] : cv_[j]);
;                     }
;                     const f32x4 hcg = bg + w0g * p2g + w1g * p1g + w2g * cg_;
;                     const f32x4 hcv = bv + w0v * p2v + w1v * p1v + w2v * cv_;
;                     const f32x2 ga = gelu_pk((f32x2){hcg[0], hcg[1]}), gb2 = gelu_pk((f32x2){hcg[2], hcg[3]});
;                     u32x2 w; w.x = cvt_pk_bf16(ga.x * hcv[0], ga.y * hcv[1]); w.y = cvt_pk_bf16(gb2.x * hcv[2], gb2.y * hcv[3]);
;                     const int t = tstart + rl;
;                     if (n == 0) stash[ai][m] = w;
;                     else if (rl >= 2) *(u32x4*)(U + (size_t)(arow0 + rl) * FF + colg0) = (u32x4){stash[ai][m].x, stash[ai][m].y, w.x, w.y};
;                     if (rl < 2 || rl >= 254) { float* hp = halo + ((size_t)u.pm * 4 + (rl < 2 ? rl : rl - 252)) * FF2; *(f32x4*)(hp + colg) = cg_; *(f32x4*)(hp + colv) = cv_; }
;                     if (t >= SEQ - 2) { float* cp = conv_p + (size_t)(b * 2 + (t - (SEQ - 2))) * FF2; *(f32x4*)(cp + colg) = cg_; *(f32x4*)(cp + colv) = cv_; }
.Lmy_p5_11:
	s_or_b64 exec, exec, s[22:23]
	v_pk_fma_f32 v[206:207], v[102:103], v[12:13], v[98:99]
	v_pk_fma_f32 v[210:211], v[92:93], v[8:9], v[84:85]
	v_pk_fma_f32 v[208:209], v[104:105], v[14:15], v[100:101]
	v_pk_fma_f32 v[212:213], v[94:95], v[10:11], v[86:87]
	v_pk_fma_f32 v[206:207], v[106:107], v[4:5], v[206:207]
	v_pk_fma_f32 v[210:211], v[88:89], v[0:1], v[210:211]
	v_pk_fma_f32 v[208:209], v[108:109], v[6:7], v[208:209]
	v_pk_fma_f32 v[212:213], v[90:91], v[2:3], v[212:213]
	v_pk_fma_f32 v[206:207], v[110:111], v[16:17], v[206:207]
	v_pk_fma_f32 v[210:211], v[80:81], v[20:21], v[210:211]
	v_pk_fma_f32 v[208:209], v[112:113], v[18:19], v[208:209]
	v_pk_fma_f32 v[212:213], v[82:83], v[22:23], v[212:213]
	v_fma_f32 v214, |v206|, s6, 1.0
	v_fma_f32 v215, |v207|, s6, 1.0
	v_pk_mul_f32 v[218:219], v[206:207], v[206:207]
	s_nop 0
	v_pk_mul_f32 v[218:219], v[218:219], s[36:37] op_sel_hi:[1,0]
	v_rcp_f32_e32 v214, v214
	v_rcp_f32_e32 v215, v215
	v_exp_f32_e32 v218, v218
	v_exp_f32_e32 v219, v219
	v_pk_fma_f32 v[216:217], v[214:215], s[24:25], v[186:187] op_sel_hi:[1,0,0]
	v_max_f32_e32 v220, 0, v206
	v_pk_fma_f32 v[216:217], v[214:215], v[216:217], s[28:29] op_sel_hi:[1,1,0]
	v_max_f32_e32 v221, 0, v207
	v_pk_fma_f32 v[216:217], v[214:215], v[216:217], s[30:31] op_sel_hi:[1,1,0]
	s_nop 0
	v_pk_fma_f32 v[216:217], v[214:215], v[216:217], s[34:35] op_sel_hi:[1,1,0]
	s_nop 0
	v_pk_mul_f32 v[216:217], v[214:215], v[216:217]
	s_nop 0
	v_pk_mul_f32 v[216:217], v[218:219], v[216:217]
	s_nop 0
	v_fma_f32 v206, -|v206|, v216, v220
	v_fma_f32 v207, -|v207|, v217, v221
	v_mul_f32_e32 v206, v210, v206
	v_mul_f32_e32 v207, v211, v207
	v_fma_f32 v214, |v208|, s6, 1.0
	v_fma_f32 v215, |v209|, s6, 1.0
	v_pk_mul_f32 v[218:219], v[208:209], v[208:209]
	s_nop 0
	v_pk_mul_f32 v[218:219], v[218:219], s[36:37] op_sel_hi:[1,0]
	v_rcp_f32_e32 v214, v214
	v_rcp_f32_e32 v215, v215
	v_exp_f32_e32 v218, v218
	v_exp_f32_e32 v219, v219
	v_pk_fma_f32 v[216:217], v[214:215], s[24:25], v[186:187] op_sel_hi:[1,0,0]
	v_max_f32_e32 v220, 0, v208
	v_pk_fma_f32 v[216:217], v[214:215], v[216:217], s[28:29] op_sel_hi:[1,1,0]
	v_max_f32_e32 v221, 0, v209
	v_pk_fma_f32 v[216:217], v[214:215], v[216:217], s[30:31] op_sel_hi:[1,1,0]
	s_nop 0
	v_pk_fma_f32 v[216:217], v[214:215], v[216:217], s[34:35] op_sel_hi:[1,1,0]
	s_nop 0
	v_pk_mul_f32 v[216:217], v[214:215], v[216:217]
	s_nop 0
	v_pk_mul_f32 v[216:217], v[218:219], v[216:217]
	s_nop 0
	v_fma_f32 v208, -|v208|, v216, v220
	v_fma_f32 v209, -|v209|, v217, v221
	v_mul_f32_e32 v208, v212, v208
	v_mul_f32_e32 v209, v213, v209
	v_mov_b64_e32 v[218:219], v[152:153]
	v_cvt_pk_bf16_f32 v220, v206, v207
	v_cvt_pk_bf16_f32 v221, v208, v209
	v_lshl_add_u64 v[126:127], s[70:71], 0, v[184:185]
	global_store_dwordx4 v[126:127], v[218:221], off nt
	s_and_saveexec_b64 s[22:23], s[76:77]
	s_cbranch_execz .Lmy_p5_12
	s_lshr_b32 s18, s16, 6
	s_add_i32 s18, s18, 3
	s_mul_i32 s18, s18, 0x5800
	s_mov_b32 s19, 0
	v_lshlrev_b64 v[214:215], 2, v[182:183]
	v_lshl_add_u64 v[214:215], s[18:19], 0, v[214:215]
	v_lshl_add_u64 v[214:215], s[92:93], 0, v[214:215]
	global_store_dwordx4 v[214:215], v[16:19], off offset:16 nt
	v_lshl_add_u64 v[216:217], v[214:215], 0, s[52:53]
	global_store_dwordx4 v[216:217], v[20:23], off offset:3088 nt
	s_bfe_u32 s18, s16, 0x60008
	s_cmp_eq_u32 s18, 63
	s_cbranch_scc0 .Lmy_p5_12
	s_lshr_b32 s18, s16, 14
	s_lshl_b32 s18, s18, 1
	s_add_i32 s18, s18, 1
	s_mul_i32 s18, s18, 0x5800
	s_mov_b32 s19, 0
	v_lshlrev_b64 v[214:215], 2, v[182:183]
	v_lshl_add_u64 v[214:215], s[18:19], 0, v[214:215]
	v_lshl_add_u64 v[214:215], s[0:1], 0, v[214:215]
	global_store_dwordx4 v[214:215], v[16:19], off offset:16 nt
	v_lshl_add_u64 v[216:217], v[214:215], 0, s[52:53]
	global_store_dwordx4 v[216:217], v[20:23], off offset:3088 nt
